# SSD producer: second unit's loads overlap first unit's compute; flag publish/wait deferred past the item setup
# baseline (speedup 1.0000x reference)
; __device__ __forceinline__ float bflo(unsigned w) { return __uint_as_float(w << 16); }
; __device__ __forceinline__ float bfhi(unsigned w) { return __uint_as_float(w & 0xffff0000u); }
; __device__ __forceinline__ void ssd_prompt_item(const Params& p, int item, const int wv) {
;     ...
;       float w[4][8], bias[8];
; #pragma unroll
;       for (int k = 0; k < 4; ++k) { f32x4 w0 = *(const f32x4*)(convw + k * 1536 + colbc), w1 = *(const f32x4*)(convw + k * 1536 + colbc + 4);
;         w[k][0] = w0[0]; w[k][1] = w0[1]; w[k][2] = w0[2]; w[k][3] = w0[3]; w[k][4] = w1[0]; w[k][5] = w1[1]; w[k][6] = w1[2]; w[k][7] = w1[3]; }
;       { f32x4 b0 = *(const f32x4*)(convb + colbc), b1 = *(const f32x4*)(convb + colbc + 4);
;         bias[0] = b0[0]; bias[1] = b0[1]; bias[2] = b0[2]; bias[3] = b0[3]; bias[4] = b1[0]; bias[5] = b1[1]; bias[6] = b1[2]; bias[7] = b1[3]; }
;       unsigned outp[8][4];
; #pragma unroll
;       for (int jj = 0; jj < 8; ++jj) {
;         float o[8];
; #pragma unroll
;         for (int e = 0; e < 8; ++e) o[e] = bias[e];
; #pragma unroll
;         for (int k = 0; k < 4; ++k) {
;           u32x4 uu = u[jj + k];
;           o[0] += w[k][0] * bflo(uu.x); o[1] += w[k][1] * bfhi(uu.x); o[2] += w[k][2] * bflo(uu.y); o[3] += w[k][3] * bfhi(uu.y);
;           o[4] += w[k][4] * bflo(uu.z); o[5] += w[k][5] * bfhi(uu.z); o[6] += w[k][6] * bflo(uu.w); o[7] += w[k][7] * bfhi(uu.w);
.LBB0_566:
	s_lshr_b32 s0, s68, 4
	s_and_b32 s1, s68, 15
	s_lshr_b32 s4, s1, 3
	s_add_u32 s8, s50, 0x72ae000
	s_addc_u32 s9, s51, 0
	s_add_u32 s10, s50, 0xa30e000
	s_addc_u32 s11, s51, 0
	v_readlane_b32 s12, v251, 48
	v_readlane_b32 s13, v251, 49
	v_readlane_b32 s18, v251, 50
	v_readlane_b32 s19, v251, 51
	v_mbcnt_lo_u32_b32 v226, -1, 0
	v_mbcnt_hi_u32_b32 v226, -1, v226
	v_add_u32_e32 v226, s82, v226
	v_and_b32_e32 v227, 31, v226
	v_lshrrev_b32_e32 v228, 5, v226
	v_lshlrev_b32_e32 v228, 3, v228
	v_and_b32_e32 v230, 15, v227
	v_lshlrev_b32_e32 v230, 3, v230
	v_and_b32_e32 v231, 16, v227
	v_lshlrev_b32_e32 v231, 4, v231
	s_lshl_b32 s20, s4, 7
	s_addk_i32 s20, 0x400
	v_add3_u32 v229, v230, v231, s20
	v_mul_u32_u24_e32 v230, 0x600, v228
	v_add_lshl_u32 v232, v230, v229, 1
	v_add_u32_e32 v233, 0x1800, v232
	v_add_u32_e32 v234, 0x3000, v232
	v_add_u32_e32 v235, 0x4800, v232
	v_add_u32_e32 v236, 0x6000, v232
	v_add_u32_e32 v237, 0x7800, v232
	v_lshlrev_b32_e32 v230, 9, v228
	v_add_u32_e32 v230, v230, v229
	v_subrev_u32_e32 v230, 0x400, v230
	v_lshlrev_b32_e32 v238, 1, v230
	v_add_u32_e32 v239, 0x1000, v238
	v_mov_b32_e32 v249, 0
	s_lshl_b32 s20, s0, 21
	v_add_u32_e32 v248, s20, v238
	s_nop 1
	v_lshl_add_u64 v[242:243], v[248:249], 0, s[10:11]
	v_lshlrev_b32_e32 v230, 2, v229
	global_load_dwordx4 v[162:165], v230, s[12:13]
	global_load_dwordx4 v[166:169], v230, s[12:13] offset:16
	v_add_u32_e32 v231, 0x1800, v230
	global_load_dwordx4 v[170:173], v231, s[12:13]
	global_load_dwordx4 v[174:177], v231, s[12:13] offset:16
	v_add_u32_e32 v231, 0x3000, v230
	global_load_dwordx4 v[178:181], v231, s[12:13]
	global_load_dwordx4 v[182:185], v231, s[12:13] offset:16
	v_add_u32_e32 v231, 0x4800, v230
	global_load_dwordx4 v[186:189], v231, s[12:13]
	global_load_dwordx4 v[190:193], v231, s[12:13] offset:16
	global_load_dwordx4 v[194:197], v230, s[18:19]
	global_load_dwordx4 v[198:201], v230, s[18:19] offset:16
	s_and_b32 s5, s1, 7
	s_lshl_b32 s5, s5, 1
	s_add_u32 s6, s5, 2
	v_cmp_le_u32_e64 s[52:53], 3, v228
	v_cmp_le_u32_e64 s[54:55], 2, v228
	v_cmp_le_u32_e64 s[56:57], 1, v228
	s_lshl_b32 s7, s0, 11
	s_lshl_b32 s20, s5, 7
	s_add_u32 s7, s7, s20
	s_sub_i32 s20, s7, 3
	s_mulk_i32 s20, 0xc00
	s_ashr_i32 s21, s20, 31
	s_add_u32 s22, s8, s20
	s_addc_u32 s23, s9, s21
	s_lshl_b32 s20, s7, 10
	s_add_u32 s24, s10, s20
	s_addc_u32 s25, s11, 0
	s_add_u32 s62, s24, 0x20000
	s_addc_u32 s63, s25, 0
	global_load_dwordx4 v[0:3], v232, s[22:23]
	global_load_dwordx4 v[4:7], v232, s[22:23] offset:3072
	global_load_dwordx4 v[8:11], v233, s[22:23]
	global_load_dwordx4 v[12:15], v233, s[22:23] offset:3072
	global_load_dwordx4 v[16:19], v234, s[22:23]
	global_load_dwordx4 v[20:23], v234, s[22:23] offset:3072
	global_load_dwordx4 v[24:27], v235, s[22:23]
	global_load_dwordx4 v[28:31], v235, s[22:23] offset:3072
	global_load_dwordx4 v[32:35], v236, s[22:23]
	global_load_dwordx4 v[36:39], v236, s[22:23] offset:3072
	global_load_dwordx4 v[40:43], v237, s[22:23]
	s_waitcnt vmcnt(0)
	s_cmp_lg_u32 s5, 0
	s_cbranch_scc1 .Lssdp_nomask
	v_cndmask_b32_e64 v0, 0, v0, s[52:53]
	v_cndmask_b32_e64 v1, 0, v1, s[52:53]
	v_cndmask_b32_e64 v2, 0, v2, s[52:53]
	v_cndmask_b32_e64 v3, 0, v3, s[52:53]
	v_cndmask_b32_e64 v4, 0, v4, s[54:55]
	v_cndmask_b32_e64 v5, 0, v5, s[54:55]
	v_cndmask_b32_e64 v6, 0, v6, s[54:55]
	v_cndmask_b32_e64 v7, 0, v7, s[54:55]
	v_cndmask_b32_e64 v8, 0, v8, s[56:57]
	v_cndmask_b32_e64 v9, 0, v9, s[56:57]
	v_cndmask_b32_e64 v10, 0, v10, s[56:57]
	v_cndmask_b32_e64 v11, 0, v11, s[56:57]
.Lssdp_nomask:
	v_lshlrev_b32_e32 v44, 16, v0
	v_and_b32_e32 v45, 0xffff0000, v0
	v_lshlrev_b32_e32 v46, 16, v1
	v_and_b32_e32 v47, 0xffff0000, v1
	v_lshlrev_b32_e32 v48, 16, v2
	v_and_b32_e32 v49, 0xffff0000, v2
	v_lshlrev_b32_e32 v50, 16, v3
	v_and_b32_e32 v51, 0xffff0000, v3
	v_lshlrev_b32_e32 v52, 16, v4
	v_and_b32_e32 v53, 0xffff0000, v4
	v_lshlrev_b32_e32 v54, 16, v5
	v_and_b32_e32 v55, 0xffff0000, v5
	v_lshlrev_b32_e32 v56, 16, v6
	v_and_b32_e32 v57, 0xffff0000, v6
	v_lshlrev_b32_e32 v58, 16, v7
	v_and_b32_e32 v59, 0xffff0000, v7
	v_lshlrev_b32_e32 v60, 16, v8
	v_and_b32_e32 v61, 0xffff0000, v8
	v_lshlrev_b32_e32 v62, 16, v9
	v_and_b32_e32 v63, 0xffff0000, v9
	v_lshlrev_b32_e32 v64, 16, v10
	v_and_b32_e32 v65, 0xffff0000, v10
	v_lshlrev_b32_e32 v66, 16, v11
	v_and_b32_e32 v67, 0xffff0000, v11
	v_lshlrev_b32_e32 v68, 16, v12
	v_and_b32_e32 v69, 0xffff0000, v12
	v_lshlrev_b32_e32 v70, 16, v13
	v_and_b32_e32 v71, 0xffff0000, v13
	v_lshlrev_b32_e32 v72, 16, v14
	v_and_b32_e32 v73, 0xffff0000, v14
	v_lshlrev_b32_e32 v74, 16, v15
	v_and_b32_e32 v75, 0xffff0000, v15
	v_lshlrev_b32_e32 v76, 16, v16
	v_and_b32_e32 v77, 0xffff0000, v16
	v_lshlrev_b32_e32 v78, 16, v17
	v_and_b32_e32 v79, 0xffff0000, v17
	v_lshlrev_b32_e32 v80, 16, v18
	v_and_b32_e32 v81, 0xffff0000, v18
	v_lshlrev_b32_e32 v82, 16, v19
	v_and_b32_e32 v83, 0xffff0000, v19
	v_lshlrev_b32_e32 v84, 16, v20
	v_and_b32_e32 v85, 0xffff0000, v20
	v_lshlrev_b32_e32 v86, 16, v21
	v_and_b32_e32 v87, 0xffff0000, v21
	v_lshlrev_b32_e32 v88, 16, v22
	v_and_b32_e32 v89, 0xffff0000, v22
	v_lshlrev_b32_e32 v90, 16, v23
	v_and_b32_e32 v91, 0xffff0000, v23
	v_lshlrev_b32_e32 v92, 16, v24
	v_and_b32_e32 v93, 0xffff0000, v24
	v_lshlrev_b32_e32 v94, 16, v25
	v_and_b32_e32 v95, 0xffff0000, v25
	v_lshlrev_b32_e32 v96, 16, v26
	v_and_b32_e32 v97, 0xffff0000, v26
	v_lshlrev_b32_e32 v98, 16, v27
	v_and_b32_e32 v99, 0xffff0000, v27
	v_lshlrev_b32_e32 v100, 16, v28
	v_and_b32_e32 v101, 0xffff0000, v28
	v_lshlrev_b32_e32 v102, 16, v29
	v_and_b32_e32 v103, 0xffff0000, v29
	v_lshlrev_b32_e32 v104, 16, v30
	v_and_b32_e32 v105, 0xffff0000, v30
	v_lshlrev_b32_e32 v106, 16, v31
; __device__ __forceinline__ unsigned cvt_pk(float lo, float hi) { f32x2 v = {lo, hi}; bf16x2_t b = __builtin_convertvector(v, bf16x2_t); return __builtin_bit_cast(unsigned, b); }
; __device__ __forceinline__ float bflo(unsigned w) { return __uint_as_float(w << 16); }
; __device__ __forceinline__ float bfhi(unsigned w) { return __uint_as_float(w & 0xffff0000u); }
; __device__ __forceinline__ float silu_f(float x) { return x * __builtin_amdgcn_rcpf(1.f + __builtin_amdgcn_exp2f(-1.4426950409f * x)); }
; __device__ __forceinline__ void ssd_prompt_item(const Params& p, int item, const int wv) {
;     ...
;       for (int jj = 0; jj < 8; ++jj) {
;         float o[8];
; #pragma unroll
;         for (int e = 0; e < 8; ++e) o[e] = bias[e];
; #pragma unroll
;         for (int k = 0; k < 4; ++k) {
;           u32x4 uu = u[jj + k];
;           o[0] += w[k][0] * bflo(uu.x); o[1] += w[k][1] * bfhi(uu.x); o[2] += w[k][2] * bflo(uu.y); o[3] += w[k][3] * bfhi(uu.y);
;           o[4] += w[k][4] * bflo(uu.z); o[5] += w[k][5] * bfhi(uu.z); o[6] += w[k][6] * bflo(uu.w); o[7] += w[k][7] * bfhi(uu.w);
;         }
; #pragma unroll
;         for (int e = 0; e < 8; ++e) o[e] = silu_f(o[e]);
; #pragma unroll
;         for (int e2 = 0; e2 < 4; ++e2) outp[jj][e2] = cvt_pk(o[2 * e2], o[2 * e2 + 1]);
;       }
	v_and_b32_e32 v107, 0xffff0000, v31
	v_lshlrev_b32_e32 v108, 16, v32
	v_and_b32_e32 v109, 0xffff0000, v32
	v_lshlrev_b32_e32 v110, 16, v33
	v_and_b32_e32 v111, 0xffff0000, v33
	v_lshlrev_b32_e32 v112, 16, v34
	v_and_b32_e32 v113, 0xffff0000, v34
	v_lshlrev_b32_e32 v114, 16, v35
	v_and_b32_e32 v115, 0xffff0000, v35
	v_lshlrev_b32_e32 v116, 16, v36
	v_and_b32_e32 v117, 0xffff0000, v36
	v_lshlrev_b32_e32 v118, 16, v37
	v_and_b32_e32 v119, 0xffff0000, v37
	v_lshlrev_b32_e32 v120, 16, v38
	v_and_b32_e32 v121, 0xffff0000, v38
	v_lshlrev_b32_e32 v122, 16, v39
	v_and_b32_e32 v123, 0xffff0000, v39
	v_lshlrev_b32_e32 v124, 16, v40
	v_and_b32_e32 v125, 0xffff0000, v40
	v_lshlrev_b32_e32 v126, 16, v41
	v_and_b32_e32 v127, 0xffff0000, v41
	v_lshlrev_b32_e32 v128, 16, v42
	v_and_b32_e32 v129, 0xffff0000, v42
	v_lshlrev_b32_e32 v130, 16, v43
	v_and_b32_e32 v131, 0xffff0000, v43
	s_add_u32 s5, s5, 1
	s_lshl_b32 s7, s0, 11
	s_lshl_b32 s20, s5, 7
	s_add_u32 s7, s7, s20
	s_sub_i32 s20, s7, 3
	s_mulk_i32 s20, 0xc00
	s_ashr_i32 s21, s20, 31
	s_add_u32 s22, s8, s20
	s_addc_u32 s23, s9, s21
	global_load_dwordx4 v[0:3], v232, s[22:23]
	global_load_dwordx4 v[4:7], v232, s[22:23] offset:3072
	global_load_dwordx4 v[8:11], v233, s[22:23]
	global_load_dwordx4 v[12:15], v233, s[22:23] offset:3072
	global_load_dwordx4 v[16:19], v234, s[22:23]
	global_load_dwordx4 v[20:23], v234, s[22:23] offset:3072
	global_load_dwordx4 v[24:27], v235, s[22:23]
	global_load_dwordx4 v[28:31], v235, s[22:23] offset:3072
	global_load_dwordx4 v[32:35], v236, s[22:23]
	global_load_dwordx4 v[36:39], v236, s[22:23] offset:3072
	global_load_dwordx4 v[40:43], v237, s[22:23]
	v_pk_fma_f32 v[202:203], v[162:163], v[44:45], v[194:195]
	v_pk_fma_f32 v[204:205], v[164:165], v[46:47], v[196:197]
	v_pk_fma_f32 v[206:207], v[166:167], v[48:49], v[198:199]
	v_pk_fma_f32 v[208:209], v[168:169], v[50:51], v[200:201]
	v_pk_fma_f32 v[202:203], v[170:171], v[52:53], v[202:203]
	v_pk_fma_f32 v[204:205], v[172:173], v[54:55], v[204:205]
	v_pk_fma_f32 v[206:207], v[174:175], v[56:57], v[206:207]
	v_pk_fma_f32 v[208:209], v[176:177], v[58:59], v[208:209]
	v_pk_fma_f32 v[202:203], v[178:179], v[60:61], v[202:203]
	v_pk_fma_f32 v[204:205], v[180:181], v[62:63], v[204:205]
	v_pk_fma_f32 v[206:207], v[182:183], v[64:65], v[206:207]
	v_pk_fma_f32 v[208:209], v[184:185], v[66:67], v[208:209]
	v_pk_fma_f32 v[202:203], v[186:187], v[68:69], v[202:203]
	v_pk_fma_f32 v[204:205], v[188:189], v[70:71], v[204:205]
	v_pk_fma_f32 v[206:207], v[190:191], v[72:73], v[206:207]
	v_pk_fma_f32 v[208:209], v[192:193], v[74:75], v[208:209]
	v_mul_f32_e32 v210, 0xbfb8aa3b, v202
	v_mul_f32_e32 v211, 0xbfb8aa3b, v203
	v_mul_f32_e32 v212, 0xbfb8aa3b, v204
	v_mul_f32_e32 v213, 0xbfb8aa3b, v205
	v_mul_f32_e32 v214, 0xbfb8aa3b, v206
	v_mul_f32_e32 v215, 0xbfb8aa3b, v207
	v_mul_f32_e32 v216, 0xbfb8aa3b, v208
	v_mul_f32_e32 v217, 0xbfb8aa3b, v209
	v_exp_f32_e32 v210, v210
	v_exp_f32_e32 v211, v211
	v_exp_f32_e32 v212, v212
	v_exp_f32_e32 v213, v213
	v_exp_f32_e32 v214, v214
	v_exp_f32_e32 v215, v215
	v_exp_f32_e32 v216, v216
	v_exp_f32_e32 v217, v217
	v_add_f32_e32 v210, 1.0, v210
	v_add_f32_e32 v211, 1.0, v211
	v_add_f32_e32 v212, 1.0, v212
	v_add_f32_e32 v213, 1.0, v213
	v_add_f32_e32 v214, 1.0, v214
	v_add_f32_e32 v215, 1.0, v215
	v_add_f32_e32 v216, 1.0, v216
	v_add_f32_e32 v217, 1.0, v217
	v_rcp_f32_e32 v210, v210
	v_rcp_f32_e32 v211, v211
	v_rcp_f32_e32 v212, v212
	v_rcp_f32_e32 v213, v213
	v_rcp_f32_e32 v214, v214
	v_rcp_f32_e32 v215, v215
	v_rcp_f32_e32 v216, v216
	v_rcp_f32_e32 v217, v217
	v_pk_mul_f32 v[202:203], v[202:203], v[210:211]
	v_pk_mul_f32 v[204:205], v[204:205], v[212:213]
	v_pk_mul_f32 v[206:207], v[206:207], v[214:215]
	v_pk_mul_f32 v[208:209], v[208:209], v[216:217]
	v_cvt_pk_bf16_f32 v218, v202, v203
	v_cvt_pk_bf16_f32 v219, v204, v205
	v_cvt_pk_bf16_f32 v220, v206, v207
	v_cvt_pk_bf16_f32 v221, v208, v209
	global_store_dwordx4 v238, v[218:221], s[24:25] sc0 sc1
	v_pk_fma_f32 v[202:203], v[162:163], v[52:53], v[194:195]
	v_pk_fma_f32 v[204:205], v[164:165], v[54:55], v[196:197]
	v_pk_fma_f32 v[206:207], v[166:167], v[56:57], v[198:199]
	v_pk_fma_f32 v[208:209], v[168:169], v[58:59], v[200:201]
	v_pk_fma_f32 v[202:203], v[170:171], v[60:61], v[202:203]
	v_pk_fma_f32 v[204:205], v[172:173], v[62:63], v[204:205]
	v_pk_fma_f32 v[206:207], v[174:175], v[64:65], v[206:207]
	v_pk_fma_f32 v[208:209], v[176:177], v[66:67], v[208:209]
	v_pk_fma_f32 v[202:203], v[178:179], v[68:69], v[202:203]
	v_pk_fma_f32 v[204:205], v[180:181], v[70:71], v[204:205]
	v_pk_fma_f32 v[206:207], v[182:183], v[72:73], v[206:207]
	v_pk_fma_f32 v[208:209], v[184:185], v[74:75], v[208:209]
	v_pk_fma_f32 v[202:203], v[186:187], v[76:77], v[202:203]
	v_pk_fma_f32 v[204:205], v[188:189], v[78:79], v[204:205]
	v_pk_fma_f32 v[206:207], v[190:191], v[80:81], v[206:207]
	v_pk_fma_f32 v[208:209], v[192:193], v[82:83], v[208:209]
	v_mul_f32_e32 v210, 0xbfb8aa3b, v202
	v_mul_f32_e32 v211, 0xbfb8aa3b, v203
	v_mul_f32_e32 v212, 0xbfb8aa3b, v204
	v_mul_f32_e32 v213, 0xbfb8aa3b, v205
	v_mul_f32_e32 v214, 0xbfb8aa3b, v206
	v_mul_f32_e32 v215, 0xbfb8aa3b, v207
	v_mul_f32_e32 v216, 0xbfb8aa3b, v208
	v_mul_f32_e32 v217, 0xbfb8aa3b, v209
	v_exp_f32_e32 v210, v210
	v_exp_f32_e32 v211, v211
	v_exp_f32_e32 v212, v212
	v_exp_f32_e32 v213, v213
	v_exp_f32_e32 v214, v214
	v_exp_f32_e32 v215, v215
	v_exp_f32_e32 v216, v216
	v_exp_f32_e32 v217, v217
	v_add_f32_e32 v210, 1.0, v210
	v_add_f32_e32 v211, 1.0, v211
	v_add_f32_e32 v212, 1.0, v212
	v_add_f32_e32 v213, 1.0, v213
	v_add_f32_e32 v214, 1.0, v214
	v_add_f32_e32 v215, 1.0, v215
	v_add_f32_e32 v216, 1.0, v216
; __device__ __forceinline__ unsigned cvt_pk(float lo, float hi) { f32x2 v = {lo, hi}; bf16x2_t b = __builtin_convertvector(v, bf16x2_t); return __builtin_bit_cast(unsigned, b); }
; __device__ __forceinline__ float bflo(unsigned w) { return __uint_as_float(w << 16); }
; __device__ __forceinline__ float bfhi(unsigned w) { return __uint_as_float(w & 0xffff0000u); }
; __device__ __forceinline__ float silu_f(float x) { return x * __builtin_amdgcn_rcpf(1.f + __builtin_amdgcn_exp2f(-1.4426950409f * x)); }
; __device__ __forceinline__ void ssd_prompt_item(const Params& p, int item, const int wv) {
;     ...
;       for (int jj = 0; jj < 8; ++jj) {
;         float o[8];
; #pragma unroll
;         for (int e = 0; e < 8; ++e) o[e] = bias[e];
; #pragma unroll
;         for (int k = 0; k < 4; ++k) {
;           u32x4 uu = u[jj + k];
;           o[0] += w[k][0] * bflo(uu.x); o[1] += w[k][1] * bfhi(uu.x); o[2] += w[k][2] * bflo(uu.y); o[3] += w[k][3] * bfhi(uu.y);
;           o[4] += w[k][4] * bflo(uu.z); o[5] += w[k][5] * bfhi(uu.z); o[6] += w[k][6] * bflo(uu.w); o[7] += w[k][7] * bfhi(uu.w);
;         }
; #pragma unroll
;         for (int e = 0; e < 8; ++e) o[e] = silu_f(o[e]);
; #pragma unroll
;         for (int e2 = 0; e2 < 4; ++e2) outp[jj][e2] = cvt_pk(o[2 * e2], o[2 * e2 + 1]);
;       }
	v_add_f32_e32 v217, 1.0, v217
	v_rcp_f32_e32 v210, v210
	v_rcp_f32_e32 v211, v211
	v_rcp_f32_e32 v212, v212
	v_rcp_f32_e32 v213, v213
	v_rcp_f32_e32 v214, v214
	v_rcp_f32_e32 v215, v215
	v_rcp_f32_e32 v216, v216
	v_rcp_f32_e32 v217, v217
	v_pk_mul_f32 v[202:203], v[202:203], v[210:211]
	v_pk_mul_f32 v[204:205], v[204:205], v[212:213]
	v_pk_mul_f32 v[206:207], v[206:207], v[214:215]
	v_pk_mul_f32 v[208:209], v[208:209], v[216:217]
	v_cvt_pk_bf16_f32 v222, v202, v203
	v_cvt_pk_bf16_f32 v223, v204, v205
	v_cvt_pk_bf16_f32 v224, v206, v207
	v_cvt_pk_bf16_f32 v225, v208, v209
	global_store_dwordx4 v238, v[222:225], s[24:25] offset:1024 sc0 sc1
	v_pk_fma_f32 v[202:203], v[162:163], v[60:61], v[194:195]
	v_pk_fma_f32 v[204:205], v[164:165], v[62:63], v[196:197]
	v_pk_fma_f32 v[206:207], v[166:167], v[64:65], v[198:199]
	v_pk_fma_f32 v[208:209], v[168:169], v[66:67], v[200:201]
	v_pk_fma_f32 v[202:203], v[170:171], v[68:69], v[202:203]
	v_pk_fma_f32 v[204:205], v[172:173], v[70:71], v[204:205]
	v_pk_fma_f32 v[206:207], v[174:175], v[72:73], v[206:207]
	v_pk_fma_f32 v[208:209], v[176:177], v[74:75], v[208:209]
	v_pk_fma_f32 v[202:203], v[178:179], v[76:77], v[202:203]
	v_pk_fma_f32 v[204:205], v[180:181], v[78:79], v[204:205]
	v_pk_fma_f32 v[206:207], v[182:183], v[80:81], v[206:207]
	v_pk_fma_f32 v[208:209], v[184:185], v[82:83], v[208:209]
	v_pk_fma_f32 v[202:203], v[186:187], v[84:85], v[202:203]
	v_pk_fma_f32 v[204:205], v[188:189], v[86:87], v[204:205]
	v_pk_fma_f32 v[206:207], v[190:191], v[88:89], v[206:207]
	v_pk_fma_f32 v[208:209], v[192:193], v[90:91], v[208:209]
	v_mul_f32_e32 v210, 0xbfb8aa3b, v202
	v_mul_f32_e32 v211, 0xbfb8aa3b, v203
	v_mul_f32_e32 v212, 0xbfb8aa3b, v204
	v_mul_f32_e32 v213, 0xbfb8aa3b, v205
	v_mul_f32_e32 v214, 0xbfb8aa3b, v206
	v_mul_f32_e32 v215, 0xbfb8aa3b, v207
	v_mul_f32_e32 v216, 0xbfb8aa3b, v208
	v_mul_f32_e32 v217, 0xbfb8aa3b, v209
	v_exp_f32_e32 v210, v210
	v_exp_f32_e32 v211, v211
	v_exp_f32_e32 v212, v212
	v_exp_f32_e32 v213, v213
	v_exp_f32_e32 v214, v214
	v_exp_f32_e32 v215, v215
	v_exp_f32_e32 v216, v216
	v_exp_f32_e32 v217, v217
	v_add_f32_e32 v210, 1.0, v210
	v_add_f32_e32 v211, 1.0, v211
	v_add_f32_e32 v212, 1.0, v212
	v_add_f32_e32 v213, 1.0, v213
	v_add_f32_e32 v214, 1.0, v214
	v_add_f32_e32 v215, 1.0, v215
	v_add_f32_e32 v216, 1.0, v216
	v_add_f32_e32 v217, 1.0, v217
	v_rcp_f32_e32 v210, v210
	v_rcp_f32_e32 v211, v211
	v_rcp_f32_e32 v212, v212
	v_rcp_f32_e32 v213, v213
	v_rcp_f32_e32 v214, v214
	v_rcp_f32_e32 v215, v215
	v_rcp_f32_e32 v216, v216
	v_rcp_f32_e32 v217, v217
	v_pk_mul_f32 v[202:203], v[202:203], v[210:211]
	v_pk_mul_f32 v[204:205], v[204:205], v[212:213]
	v_pk_mul_f32 v[206:207], v[206:207], v[214:215]
	v_pk_mul_f32 v[208:209], v[208:209], v[216:217]
	v_cvt_pk_bf16_f32 v218, v202, v203
	v_cvt_pk_bf16_f32 v219, v204, v205
	v_cvt_pk_bf16_f32 v220, v206, v207
	v_cvt_pk_bf16_f32 v221, v208, v209
	global_store_dwordx4 v238, v[218:221], s[24:25] offset:2048 sc0 sc1
	v_pk_fma_f32 v[202:203], v[162:163], v[68:69], v[194:195]
	v_pk_fma_f32 v[204:205], v[164:165], v[70:71], v[196:197]
	v_pk_fma_f32 v[206:207], v[166:167], v[72:73], v[198:199]
	v_pk_fma_f32 v[208:209], v[168:169], v[74:75], v[200:201]
	v_pk_fma_f32 v[202:203], v[170:171], v[76:77], v[202:203]
	v_pk_fma_f32 v[204:205], v[172:173], v[78:79], v[204:205]
	v_pk_fma_f32 v[206:207], v[174:175], v[80:81], v[206:207]
	v_pk_fma_f32 v[208:209], v[176:177], v[82:83], v[208:209]
	v_pk_fma_f32 v[202:203], v[178:179], v[84:85], v[202:203]
	v_pk_fma_f32 v[204:205], v[180:181], v[86:87], v[204:205]
	v_pk_fma_f32 v[206:207], v[182:183], v[88:89], v[206:207]
	v_pk_fma_f32 v[208:209], v[184:185], v[90:91], v[208:209]
	v_pk_fma_f32 v[202:203], v[186:187], v[92:93], v[202:203]
	v_pk_fma_f32 v[204:205], v[188:189], v[94:95], v[204:205]
	v_pk_fma_f32 v[206:207], v[190:191], v[96:97], v[206:207]
	v_pk_fma_f32 v[208:209], v[192:193], v[98:99], v[208:209]
	v_mul_f32_e32 v210, 0xbfb8aa3b, v202
	v_mul_f32_e32 v211, 0xbfb8aa3b, v203
	v_mul_f32_e32 v212, 0xbfb8aa3b, v204
	v_mul_f32_e32 v213, 0xbfb8aa3b, v205
	v_mul_f32_e32 v214, 0xbfb8aa3b, v206
	v_mul_f32_e32 v215, 0xbfb8aa3b, v207
	v_mul_f32_e32 v216, 0xbfb8aa3b, v208
	v_mul_f32_e32 v217, 0xbfb8aa3b, v209
	v_exp_f32_e32 v210, v210
	v_exp_f32_e32 v211, v211
	v_exp_f32_e32 v212, v212
	v_exp_f32_e32 v213, v213
	v_exp_f32_e32 v214, v214
	v_exp_f32_e32 v215, v215
	v_exp_f32_e32 v216, v216
	v_exp_f32_e32 v217, v217
	v_add_f32_e32 v210, 1.0, v210
	v_add_f32_e32 v211, 1.0, v211
	v_add_f32_e32 v212, 1.0, v212
	v_add_f32_e32 v213, 1.0, v213
	v_add_f32_e32 v214, 1.0, v214
	v_add_f32_e32 v215, 1.0, v215
	v_add_f32_e32 v216, 1.0, v216
	v_add_f32_e32 v217, 1.0, v217
	v_rcp_f32_e32 v210, v210
	v_rcp_f32_e32 v211, v211
	v_rcp_f32_e32 v212, v212
	v_rcp_f32_e32 v213, v213
	v_rcp_f32_e32 v214, v214
	v_rcp_f32_e32 v215, v215
	v_rcp_f32_e32 v216, v216
	v_rcp_f32_e32 v217, v217
	v_pk_mul_f32 v[202:203], v[202:203], v[210:211]
	v_pk_mul_f32 v[204:205], v[204:205], v[212:213]
	v_pk_mul_f32 v[206:207], v[206:207], v[214:215]
	v_pk_mul_f32 v[208:209], v[208:209], v[216:217]
	v_cvt_pk_bf16_f32 v222, v202, v203
	v_cvt_pk_bf16_f32 v223, v204, v205
	v_cvt_pk_bf16_f32 v224, v206, v207
	v_cvt_pk_bf16_f32 v225, v208, v209
	global_store_dwordx4 v238, v[222:225], s[24:25] offset:3072 sc0 sc1
	v_pk_fma_f32 v[202:203], v[162:163], v[76:77], v[194:195]
	v_pk_fma_f32 v[204:205], v[164:165], v[78:79], v[196:197]
	v_pk_fma_f32 v[206:207], v[166:167], v[80:81], v[198:199]
	v_pk_fma_f32 v[208:209], v[168:169], v[82:83], v[200:201]
	v_pk_fma_f32 v[202:203], v[170:171], v[84:85], v[202:203]
	v_pk_fma_f32 v[204:205], v[172:173], v[86:87], v[204:205]
; __device__ __forceinline__ unsigned cvt_pk(float lo, float hi) { f32x2 v = {lo, hi}; bf16x2_t b = __builtin_convertvector(v, bf16x2_t); return __builtin_bit_cast(unsigned, b); }
; __device__ __forceinline__ float bflo(unsigned w) { return __uint_as_float(w << 16); }
; __device__ __forceinline__ float bfhi(unsigned w) { return __uint_as_float(w & 0xffff0000u); }
; __device__ __forceinline__ float silu_f(float x) { return x * __builtin_amdgcn_rcpf(1.f + __builtin_amdgcn_exp2f(-1.4426950409f * x)); }
; __device__ __forceinline__ void ssd_prompt_item(const Params& p, int item, const int wv) {
;     ...
;       for (int jj = 0; jj < 8; ++jj) {
;         float o[8];
; #pragma unroll
;         for (int e = 0; e < 8; ++e) o[e] = bias[e];
; #pragma unroll
;         for (int k = 0; k < 4; ++k) {
;           u32x4 uu = u[jj + k];
;           o[0] += w[k][0] * bflo(uu.x); o[1] += w[k][1] * bfhi(uu.x); o[2] += w[k][2] * bflo(uu.y); o[3] += w[k][3] * bfhi(uu.y);
;           o[4] += w[k][4] * bflo(uu.z); o[5] += w[k][5] * bfhi(uu.z); o[6] += w[k][6] * bflo(uu.w); o[7] += w[k][7] * bfhi(uu.w);
;         }
; #pragma unroll
;         for (int e = 0; e < 8; ++e) o[e] = silu_f(o[e]);
; #pragma unroll
;         for (int e2 = 0; e2 < 4; ++e2) outp[jj][e2] = cvt_pk(o[2 * e2], o[2 * e2 + 1]);
;       }
	v_pk_fma_f32 v[206:207], v[174:175], v[88:89], v[206:207]
	v_pk_fma_f32 v[208:209], v[176:177], v[90:91], v[208:209]
	v_pk_fma_f32 v[202:203], v[178:179], v[92:93], v[202:203]
	v_pk_fma_f32 v[204:205], v[180:181], v[94:95], v[204:205]
	v_pk_fma_f32 v[206:207], v[182:183], v[96:97], v[206:207]
	v_pk_fma_f32 v[208:209], v[184:185], v[98:99], v[208:209]
	v_pk_fma_f32 v[202:203], v[186:187], v[100:101], v[202:203]
	v_pk_fma_f32 v[204:205], v[188:189], v[102:103], v[204:205]
	v_pk_fma_f32 v[206:207], v[190:191], v[104:105], v[206:207]
	v_pk_fma_f32 v[208:209], v[192:193], v[106:107], v[208:209]
	v_mul_f32_e32 v210, 0xbfb8aa3b, v202
	v_mul_f32_e32 v211, 0xbfb8aa3b, v203
	v_mul_f32_e32 v212, 0xbfb8aa3b, v204
	v_mul_f32_e32 v213, 0xbfb8aa3b, v205
	v_mul_f32_e32 v214, 0xbfb8aa3b, v206
	v_mul_f32_e32 v215, 0xbfb8aa3b, v207
	v_mul_f32_e32 v216, 0xbfb8aa3b, v208
	v_mul_f32_e32 v217, 0xbfb8aa3b, v209
	v_exp_f32_e32 v210, v210
	v_exp_f32_e32 v211, v211
	v_exp_f32_e32 v212, v212
	v_exp_f32_e32 v213, v213
	v_exp_f32_e32 v214, v214
	v_exp_f32_e32 v215, v215
	v_exp_f32_e32 v216, v216
	v_exp_f32_e32 v217, v217
	v_add_f32_e32 v210, 1.0, v210
	v_add_f32_e32 v211, 1.0, v211
	v_add_f32_e32 v212, 1.0, v212
	v_add_f32_e32 v213, 1.0, v213
	v_add_f32_e32 v214, 1.0, v214
	v_add_f32_e32 v215, 1.0, v215
	v_add_f32_e32 v216, 1.0, v216
	v_add_f32_e32 v217, 1.0, v217
	v_rcp_f32_e32 v210, v210
	v_rcp_f32_e32 v211, v211
	v_rcp_f32_e32 v212, v212
	v_rcp_f32_e32 v213, v213
	v_rcp_f32_e32 v214, v214
	v_rcp_f32_e32 v215, v215
	v_rcp_f32_e32 v216, v216
	v_rcp_f32_e32 v217, v217
	v_pk_mul_f32 v[202:203], v[202:203], v[210:211]
	v_pk_mul_f32 v[204:205], v[204:205], v[212:213]
	v_pk_mul_f32 v[206:207], v[206:207], v[214:215]
	v_pk_mul_f32 v[208:209], v[208:209], v[216:217]
	v_cvt_pk_bf16_f32 v218, v202, v203
	v_cvt_pk_bf16_f32 v219, v204, v205
	v_cvt_pk_bf16_f32 v220, v206, v207
	v_cvt_pk_bf16_f32 v221, v208, v209
	global_store_dwordx4 v239, v[218:221], s[24:25] sc0 sc1
	v_pk_fma_f32 v[202:203], v[162:163], v[84:85], v[194:195]
	v_pk_fma_f32 v[204:205], v[164:165], v[86:87], v[196:197]
	v_pk_fma_f32 v[206:207], v[166:167], v[88:89], v[198:199]
	v_pk_fma_f32 v[208:209], v[168:169], v[90:91], v[200:201]
	v_pk_fma_f32 v[202:203], v[170:171], v[92:93], v[202:203]
	v_pk_fma_f32 v[204:205], v[172:173], v[94:95], v[204:205]
	v_pk_fma_f32 v[206:207], v[174:175], v[96:97], v[206:207]
	v_pk_fma_f32 v[208:209], v[176:177], v[98:99], v[208:209]
	v_pk_fma_f32 v[202:203], v[178:179], v[100:101], v[202:203]
	v_pk_fma_f32 v[204:205], v[180:181], v[102:103], v[204:205]
	v_pk_fma_f32 v[206:207], v[182:183], v[104:105], v[206:207]
	v_pk_fma_f32 v[208:209], v[184:185], v[106:107], v[208:209]
	v_pk_fma_f32 v[202:203], v[186:187], v[108:109], v[202:203]
	v_pk_fma_f32 v[204:205], v[188:189], v[110:111], v[204:205]
	v_pk_fma_f32 v[206:207], v[190:191], v[112:113], v[206:207]
	v_pk_fma_f32 v[208:209], v[192:193], v[114:115], v[208:209]
	v_mul_f32_e32 v210, 0xbfb8aa3b, v202
	v_mul_f32_e32 v211, 0xbfb8aa3b, v203
	v_mul_f32_e32 v212, 0xbfb8aa3b, v204
	v_mul_f32_e32 v213, 0xbfb8aa3b, v205
	v_mul_f32_e32 v214, 0xbfb8aa3b, v206
	v_mul_f32_e32 v215, 0xbfb8aa3b, v207
	v_mul_f32_e32 v216, 0xbfb8aa3b, v208
	v_mul_f32_e32 v217, 0xbfb8aa3b, v209
	v_exp_f32_e32 v210, v210
	v_exp_f32_e32 v211, v211
	v_exp_f32_e32 v212, v212
	v_exp_f32_e32 v213, v213
	v_exp_f32_e32 v214, v214
	v_exp_f32_e32 v215, v215
	v_exp_f32_e32 v216, v216
	v_exp_f32_e32 v217, v217
	v_add_f32_e32 v210, 1.0, v210
	v_add_f32_e32 v211, 1.0, v211
	v_add_f32_e32 v212, 1.0, v212
	v_add_f32_e32 v213, 1.0, v213
	v_add_f32_e32 v214, 1.0, v214
	v_add_f32_e32 v215, 1.0, v215
	v_add_f32_e32 v216, 1.0, v216
	v_add_f32_e32 v217, 1.0, v217
	v_rcp_f32_e32 v210, v210
	v_rcp_f32_e32 v211, v211
	v_rcp_f32_e32 v212, v212
	v_rcp_f32_e32 v213, v213
	v_rcp_f32_e32 v214, v214
	v_rcp_f32_e32 v215, v215
	v_rcp_f32_e32 v216, v216
	v_rcp_f32_e32 v217, v217
	v_pk_mul_f32 v[202:203], v[202:203], v[210:211]
	v_pk_mul_f32 v[204:205], v[204:205], v[212:213]
	v_pk_mul_f32 v[206:207], v[206:207], v[214:215]
	v_pk_mul_f32 v[208:209], v[208:209], v[216:217]
	v_cvt_pk_bf16_f32 v222, v202, v203
	v_cvt_pk_bf16_f32 v223, v204, v205
	v_cvt_pk_bf16_f32 v224, v206, v207
	v_cvt_pk_bf16_f32 v225, v208, v209
	global_store_dwordx4 v239, v[222:225], s[24:25] offset:1024 sc0 sc1
	v_pk_fma_f32 v[202:203], v[162:163], v[92:93], v[194:195]
	v_pk_fma_f32 v[204:205], v[164:165], v[94:95], v[196:197]
	v_pk_fma_f32 v[206:207], v[166:167], v[96:97], v[198:199]
	v_pk_fma_f32 v[208:209], v[168:169], v[98:99], v[200:201]
	v_pk_fma_f32 v[202:203], v[170:171], v[100:101], v[202:203]
	v_pk_fma_f32 v[204:205], v[172:173], v[102:103], v[204:205]
	v_pk_fma_f32 v[206:207], v[174:175], v[104:105], v[206:207]
	v_pk_fma_f32 v[208:209], v[176:177], v[106:107], v[208:209]
	v_pk_fma_f32 v[202:203], v[178:179], v[108:109], v[202:203]
	v_pk_fma_f32 v[204:205], v[180:181], v[110:111], v[204:205]
	v_pk_fma_f32 v[206:207], v[182:183], v[112:113], v[206:207]
	v_pk_fma_f32 v[208:209], v[184:185], v[114:115], v[208:209]
	v_pk_fma_f32 v[202:203], v[186:187], v[116:117], v[202:203]
	v_pk_fma_f32 v[204:205], v[188:189], v[118:119], v[204:205]
	v_pk_fma_f32 v[206:207], v[190:191], v[120:121], v[206:207]
	v_pk_fma_f32 v[208:209], v[192:193], v[122:123], v[208:209]
	v_mul_f32_e32 v210, 0xbfb8aa3b, v202
	v_mul_f32_e32 v211, 0xbfb8aa3b, v203
	v_mul_f32_e32 v212, 0xbfb8aa3b, v204
	v_mul_f32_e32 v213, 0xbfb8aa3b, v205
	v_mul_f32_e32 v214, 0xbfb8aa3b, v206
	v_mul_f32_e32 v215, 0xbfb8aa3b, v207
	v_mul_f32_e32 v216, 0xbfb8aa3b, v208
	v_mul_f32_e32 v217, 0xbfb8aa3b, v209
	v_exp_f32_e32 v210, v210
	v_exp_f32_e32 v211, v211
	v_exp_f32_e32 v212, v212
; __device__ __forceinline__ unsigned cvt_pk(float lo, float hi) { f32x2 v = {lo, hi}; bf16x2_t b = __builtin_convertvector(v, bf16x2_t); return __builtin_bit_cast(unsigned, b); }
; __device__ __forceinline__ float bflo(unsigned w) { return __uint_as_float(w << 16); }
; __device__ __forceinline__ float bfhi(unsigned w) { return __uint_as_float(w & 0xffff0000u); }
; __device__ __forceinline__ float silu_f(float x) { return x * __builtin_amdgcn_rcpf(1.f + __builtin_amdgcn_exp2f(-1.4426950409f * x)); }
; __device__ __forceinline__ void ssd_prompt_item(const Params& p, int item, const int wv) {
;     ...
;       for (int jj = 0; jj < 8; ++jj) {
;         float o[8];
; #pragma unroll
;         for (int e = 0; e < 8; ++e) o[e] = bias[e];
; #pragma unroll
;         for (int k = 0; k < 4; ++k) {
;           u32x4 uu = u[jj + k];
;           o[0] += w[k][0] * bflo(uu.x); o[1] += w[k][1] * bfhi(uu.x); o[2] += w[k][2] * bflo(uu.y); o[3] += w[k][3] * bfhi(uu.y);
;           o[4] += w[k][4] * bflo(uu.z); o[5] += w[k][5] * bfhi(uu.z); o[6] += w[k][6] * bflo(uu.w); o[7] += w[k][7] * bfhi(uu.w);
;         }
; #pragma unroll
;         for (int e = 0; e < 8; ++e) o[e] = silu_f(o[e]);
; #pragma unroll
;         for (int e2 = 0; e2 < 4; ++e2) outp[jj][e2] = cvt_pk(o[2 * e2], o[2 * e2 + 1]);
;       }
	v_exp_f32_e32 v213, v213
	v_exp_f32_e32 v214, v214
	v_exp_f32_e32 v215, v215
	v_exp_f32_e32 v216, v216
	v_exp_f32_e32 v217, v217
	v_add_f32_e32 v210, 1.0, v210
	v_add_f32_e32 v211, 1.0, v211
	v_add_f32_e32 v212, 1.0, v212
	v_add_f32_e32 v213, 1.0, v213
	v_add_f32_e32 v214, 1.0, v214
	v_add_f32_e32 v215, 1.0, v215
	v_add_f32_e32 v216, 1.0, v216
	v_add_f32_e32 v217, 1.0, v217
	v_rcp_f32_e32 v210, v210
	v_rcp_f32_e32 v211, v211
	v_rcp_f32_e32 v212, v212
	v_rcp_f32_e32 v213, v213
	v_rcp_f32_e32 v214, v214
	v_rcp_f32_e32 v215, v215
	v_rcp_f32_e32 v216, v216
	v_rcp_f32_e32 v217, v217
	v_pk_mul_f32 v[202:203], v[202:203], v[210:211]
	v_pk_mul_f32 v[204:205], v[204:205], v[212:213]
	v_pk_mul_f32 v[206:207], v[206:207], v[214:215]
	v_pk_mul_f32 v[208:209], v[208:209], v[216:217]
	v_cvt_pk_bf16_f32 v218, v202, v203
	v_cvt_pk_bf16_f32 v219, v204, v205
	v_cvt_pk_bf16_f32 v220, v206, v207
	v_cvt_pk_bf16_f32 v221, v208, v209
	global_store_dwordx4 v239, v[218:221], s[24:25] offset:2048 sc0 sc1
	v_pk_fma_f32 v[202:203], v[162:163], v[100:101], v[194:195]
	v_pk_fma_f32 v[204:205], v[164:165], v[102:103], v[196:197]
	v_pk_fma_f32 v[206:207], v[166:167], v[104:105], v[198:199]
	v_pk_fma_f32 v[208:209], v[168:169], v[106:107], v[200:201]
	v_pk_fma_f32 v[202:203], v[170:171], v[108:109], v[202:203]
	v_pk_fma_f32 v[204:205], v[172:173], v[110:111], v[204:205]
	v_pk_fma_f32 v[206:207], v[174:175], v[112:113], v[206:207]
	v_pk_fma_f32 v[208:209], v[176:177], v[114:115], v[208:209]
	v_pk_fma_f32 v[202:203], v[178:179], v[116:117], v[202:203]
	v_pk_fma_f32 v[204:205], v[180:181], v[118:119], v[204:205]
	v_pk_fma_f32 v[206:207], v[182:183], v[120:121], v[206:207]
	v_pk_fma_f32 v[208:209], v[184:185], v[122:123], v[208:209]
	v_pk_fma_f32 v[202:203], v[186:187], v[124:125], v[202:203]
	v_pk_fma_f32 v[204:205], v[188:189], v[126:127], v[204:205]
	v_pk_fma_f32 v[206:207], v[190:191], v[128:129], v[206:207]
	v_pk_fma_f32 v[208:209], v[192:193], v[130:131], v[208:209]
	v_mul_f32_e32 v210, 0xbfb8aa3b, v202
	v_mul_f32_e32 v211, 0xbfb8aa3b, v203
	v_mul_f32_e32 v212, 0xbfb8aa3b, v204
	v_mul_f32_e32 v213, 0xbfb8aa3b, v205
	v_mul_f32_e32 v214, 0xbfb8aa3b, v206
	v_mul_f32_e32 v215, 0xbfb8aa3b, v207
	v_mul_f32_e32 v216, 0xbfb8aa3b, v208
	v_mul_f32_e32 v217, 0xbfb8aa3b, v209
	v_exp_f32_e32 v210, v210
	v_exp_f32_e32 v211, v211
	v_exp_f32_e32 v212, v212
	v_exp_f32_e32 v213, v213
	v_exp_f32_e32 v214, v214
	v_exp_f32_e32 v215, v215
	v_exp_f32_e32 v216, v216
	v_exp_f32_e32 v217, v217
	v_add_f32_e32 v210, 1.0, v210
	v_add_f32_e32 v211, 1.0, v211
	v_add_f32_e32 v212, 1.0, v212
	v_add_f32_e32 v213, 1.0, v213
	v_add_f32_e32 v214, 1.0, v214
	v_add_f32_e32 v215, 1.0, v215
	v_add_f32_e32 v216, 1.0, v216
	v_add_f32_e32 v217, 1.0, v217
	v_rcp_f32_e32 v210, v210
	v_rcp_f32_e32 v211, v211
	v_rcp_f32_e32 v212, v212
	v_rcp_f32_e32 v213, v213
	v_rcp_f32_e32 v214, v214
	v_rcp_f32_e32 v215, v215
	v_rcp_f32_e32 v216, v216
	v_rcp_f32_e32 v217, v217
	v_pk_mul_f32 v[202:203], v[202:203], v[210:211]
	v_pk_mul_f32 v[204:205], v[204:205], v[212:213]
	v_pk_mul_f32 v[206:207], v[206:207], v[214:215]
	v_pk_mul_f32 v[208:209], v[208:209], v[216:217]
	v_cvt_pk_bf16_f32 v222, v202, v203
	v_cvt_pk_bf16_f32 v223, v204, v205
	v_cvt_pk_bf16_f32 v224, v206, v207
	v_cvt_pk_bf16_f32 v225, v208, v209
	global_store_dwordx4 v239, v[222:225], s[24:25] offset:3072 sc0 sc1
	s_waitcnt vmcnt(8)
	v_lshlrev_b32_e32 v44, 16, v0
	v_and_b32_e32 v45, 0xffff0000, v0
	v_lshlrev_b32_e32 v46, 16, v1
	v_and_b32_e32 v47, 0xffff0000, v1
	v_lshlrev_b32_e32 v48, 16, v2
	v_and_b32_e32 v49, 0xffff0000, v2
	v_lshlrev_b32_e32 v50, 16, v3
	v_and_b32_e32 v51, 0xffff0000, v3
	v_lshlrev_b32_e32 v52, 16, v4
	v_and_b32_e32 v53, 0xffff0000, v4
	v_lshlrev_b32_e32 v54, 16, v5
	v_and_b32_e32 v55, 0xffff0000, v5
	v_lshlrev_b32_e32 v56, 16, v6
	v_and_b32_e32 v57, 0xffff0000, v6
	v_lshlrev_b32_e32 v58, 16, v7
	v_and_b32_e32 v59, 0xffff0000, v7
	v_lshlrev_b32_e32 v60, 16, v8
	v_and_b32_e32 v61, 0xffff0000, v8
	v_lshlrev_b32_e32 v62, 16, v9
	v_and_b32_e32 v63, 0xffff0000, v9
	v_lshlrev_b32_e32 v64, 16, v10
	v_and_b32_e32 v65, 0xffff0000, v10
	v_lshlrev_b32_e32 v66, 16, v11
	v_and_b32_e32 v67, 0xffff0000, v11
	v_lshlrev_b32_e32 v68, 16, v12
	v_and_b32_e32 v69, 0xffff0000, v12
	v_lshlrev_b32_e32 v70, 16, v13
	v_and_b32_e32 v71, 0xffff0000, v13
	v_lshlrev_b32_e32 v72, 16, v14
	v_and_b32_e32 v73, 0xffff0000, v14
	v_lshlrev_b32_e32 v74, 16, v15
	v_and_b32_e32 v75, 0xffff0000, v15
	v_lshlrev_b32_e32 v76, 16, v16
	v_and_b32_e32 v77, 0xffff0000, v16
	v_lshlrev_b32_e32 v78, 16, v17
	v_and_b32_e32 v79, 0xffff0000, v17
	v_lshlrev_b32_e32 v80, 16, v18
	v_and_b32_e32 v81, 0xffff0000, v18
	v_lshlrev_b32_e32 v82, 16, v19
	v_and_b32_e32 v83, 0xffff0000, v19
	v_lshlrev_b32_e32 v84, 16, v20
	v_and_b32_e32 v85, 0xffff0000, v20
	v_lshlrev_b32_e32 v86, 16, v21
	v_and_b32_e32 v87, 0xffff0000, v21
	v_lshlrev_b32_e32 v88, 16, v22
	v_and_b32_e32 v89, 0xffff0000, v22
	v_lshlrev_b32_e32 v90, 16, v23
	v_and_b32_e32 v91, 0xffff0000, v23
	v_lshlrev_b32_e32 v92, 16, v24
	v_and_b32_e32 v93, 0xffff0000, v24
	v_lshlrev_b32_e32 v94, 16, v25
	v_and_b32_e32 v95, 0xffff0000, v25
	v_lshlrev_b32_e32 v96, 16, v26
	v_and_b32_e32 v97, 0xffff0000, v26
	v_lshlrev_b32_e32 v98, 16, v27
	v_and_b32_e32 v99, 0xffff0000, v27
	v_lshlrev_b32_e32 v100, 16, v28
	v_and_b32_e32 v101, 0xffff0000, v28
	v_lshlrev_b32_e32 v102, 16, v29
	v_and_b32_e32 v103, 0xffff0000, v29
	v_lshlrev_b32_e32 v104, 16, v30
	v_and_b32_e32 v105, 0xffff0000, v30
	v_lshlrev_b32_e32 v106, 16, v31
	v_and_b32_e32 v107, 0xffff0000, v31
	v_lshlrev_b32_e32 v108, 16, v32
	v_and_b32_e32 v109, 0xffff0000, v32
	v_lshlrev_b32_e32 v110, 16, v33
; __device__ __forceinline__ unsigned cvt_pk(float lo, float hi) { f32x2 v = {lo, hi}; bf16x2_t b = __builtin_convertvector(v, bf16x2_t); return __builtin_bit_cast(unsigned, b); }
; __device__ __forceinline__ float bflo(unsigned w) { return __uint_as_float(w << 16); }
; __device__ __forceinline__ float bfhi(unsigned w) { return __uint_as_float(w & 0xffff0000u); }
; __device__ __forceinline__ float silu_f(float x) { return x * __builtin_amdgcn_rcpf(1.f + __builtin_amdgcn_exp2f(-1.4426950409f * x)); }
; __device__ __forceinline__ void ssd_prompt_item(const Params& p, int item, const int wv) {
;     ...
;       for (int jj = 0; jj < 8; ++jj) {
;         float o[8];
; #pragma unroll
;         for (int e = 0; e < 8; ++e) o[e] = bias[e];
; #pragma unroll
;         for (int k = 0; k < 4; ++k) {
;           u32x4 uu = u[jj + k];
;           o[0] += w[k][0] * bflo(uu.x); o[1] += w[k][1] * bfhi(uu.x); o[2] += w[k][2] * bflo(uu.y); o[3] += w[k][3] * bfhi(uu.y);
;           o[4] += w[k][4] * bflo(uu.z); o[5] += w[k][5] * bfhi(uu.z); o[6] += w[k][6] * bflo(uu.w); o[7] += w[k][7] * bfhi(uu.w);
;         }
; #pragma unroll
;         for (int e = 0; e < 8; ++e) o[e] = silu_f(o[e]);
; #pragma unroll
;         for (int e2 = 0; e2 < 4; ++e2) outp[jj][e2] = cvt_pk(o[2 * e2], o[2 * e2 + 1]);
;       }
	v_and_b32_e32 v111, 0xffff0000, v33
	v_lshlrev_b32_e32 v112, 16, v34
	v_and_b32_e32 v113, 0xffff0000, v34
	v_lshlrev_b32_e32 v114, 16, v35
	v_and_b32_e32 v115, 0xffff0000, v35
	v_lshlrev_b32_e32 v116, 16, v36
	v_and_b32_e32 v117, 0xffff0000, v36
	v_lshlrev_b32_e32 v118, 16, v37
	v_and_b32_e32 v119, 0xffff0000, v37
	v_lshlrev_b32_e32 v120, 16, v38
	v_and_b32_e32 v121, 0xffff0000, v38
	v_lshlrev_b32_e32 v122, 16, v39
	v_and_b32_e32 v123, 0xffff0000, v39
	v_lshlrev_b32_e32 v124, 16, v40
	v_and_b32_e32 v125, 0xffff0000, v40
	v_lshlrev_b32_e32 v126, 16, v41
	v_and_b32_e32 v127, 0xffff0000, v41
	v_lshlrev_b32_e32 v128, 16, v42
	v_and_b32_e32 v129, 0xffff0000, v42
	v_lshlrev_b32_e32 v130, 16, v43
	v_and_b32_e32 v131, 0xffff0000, v43
	v_pk_fma_f32 v[202:203], v[162:163], v[44:45], v[194:195]
	v_pk_fma_f32 v[204:205], v[164:165], v[46:47], v[196:197]
	v_pk_fma_f32 v[206:207], v[166:167], v[48:49], v[198:199]
	v_pk_fma_f32 v[208:209], v[168:169], v[50:51], v[200:201]
	v_pk_fma_f32 v[202:203], v[170:171], v[52:53], v[202:203]
	v_pk_fma_f32 v[204:205], v[172:173], v[54:55], v[204:205]
	v_pk_fma_f32 v[206:207], v[174:175], v[56:57], v[206:207]
	v_pk_fma_f32 v[208:209], v[176:177], v[58:59], v[208:209]
	v_pk_fma_f32 v[202:203], v[178:179], v[60:61], v[202:203]
	v_pk_fma_f32 v[204:205], v[180:181], v[62:63], v[204:205]
	v_pk_fma_f32 v[206:207], v[182:183], v[64:65], v[206:207]
	v_pk_fma_f32 v[208:209], v[184:185], v[66:67], v[208:209]
	v_pk_fma_f32 v[202:203], v[186:187], v[68:69], v[202:203]
	v_pk_fma_f32 v[204:205], v[188:189], v[70:71], v[204:205]
	v_pk_fma_f32 v[206:207], v[190:191], v[72:73], v[206:207]
	v_pk_fma_f32 v[208:209], v[192:193], v[74:75], v[208:209]
	v_mul_f32_e32 v210, 0xbfb8aa3b, v202
	v_mul_f32_e32 v211, 0xbfb8aa3b, v203
	v_mul_f32_e32 v212, 0xbfb8aa3b, v204
	v_mul_f32_e32 v213, 0xbfb8aa3b, v205
	v_mul_f32_e32 v214, 0xbfb8aa3b, v206
	v_mul_f32_e32 v215, 0xbfb8aa3b, v207
	v_mul_f32_e32 v216, 0xbfb8aa3b, v208
	v_mul_f32_e32 v217, 0xbfb8aa3b, v209
	v_exp_f32_e32 v210, v210
	v_exp_f32_e32 v211, v211
	v_exp_f32_e32 v212, v212
	v_exp_f32_e32 v213, v213
	v_exp_f32_e32 v214, v214
	v_exp_f32_e32 v215, v215
	v_exp_f32_e32 v216, v216
	v_exp_f32_e32 v217, v217
	v_add_f32_e32 v210, 1.0, v210
	v_add_f32_e32 v211, 1.0, v211
	v_add_f32_e32 v212, 1.0, v212
	v_add_f32_e32 v213, 1.0, v213
	v_add_f32_e32 v214, 1.0, v214
	v_add_f32_e32 v215, 1.0, v215
	v_add_f32_e32 v216, 1.0, v216
	v_add_f32_e32 v217, 1.0, v217
	v_rcp_f32_e32 v210, v210
	v_rcp_f32_e32 v211, v211
	v_rcp_f32_e32 v212, v212
	v_rcp_f32_e32 v213, v213
	v_rcp_f32_e32 v214, v214
	v_rcp_f32_e32 v215, v215
	v_rcp_f32_e32 v216, v216
	v_rcp_f32_e32 v217, v217
	v_pk_mul_f32 v[202:203], v[202:203], v[210:211]
	v_pk_mul_f32 v[204:205], v[204:205], v[212:213]
	v_pk_mul_f32 v[206:207], v[206:207], v[214:215]
	v_pk_mul_f32 v[208:209], v[208:209], v[216:217]
	v_cvt_pk_bf16_f32 v218, v202, v203
	v_cvt_pk_bf16_f32 v219, v204, v205
	v_cvt_pk_bf16_f32 v220, v206, v207
	v_cvt_pk_bf16_f32 v221, v208, v209
	global_store_dwordx4 v238, v[218:221], s[62:63] sc0 sc1
	v_pk_fma_f32 v[202:203], v[162:163], v[52:53], v[194:195]
	v_pk_fma_f32 v[204:205], v[164:165], v[54:55], v[196:197]
	v_pk_fma_f32 v[206:207], v[166:167], v[56:57], v[198:199]
	v_pk_fma_f32 v[208:209], v[168:169], v[58:59], v[200:201]
	v_pk_fma_f32 v[202:203], v[170:171], v[60:61], v[202:203]
	v_pk_fma_f32 v[204:205], v[172:173], v[62:63], v[204:205]
	v_pk_fma_f32 v[206:207], v[174:175], v[64:65], v[206:207]
	v_pk_fma_f32 v[208:209], v[176:177], v[66:67], v[208:209]
	v_pk_fma_f32 v[202:203], v[178:179], v[68:69], v[202:203]
	v_pk_fma_f32 v[204:205], v[180:181], v[70:71], v[204:205]
	v_pk_fma_f32 v[206:207], v[182:183], v[72:73], v[206:207]
	v_pk_fma_f32 v[208:209], v[184:185], v[74:75], v[208:209]
	v_pk_fma_f32 v[202:203], v[186:187], v[76:77], v[202:203]
	v_pk_fma_f32 v[204:205], v[188:189], v[78:79], v[204:205]
	v_pk_fma_f32 v[206:207], v[190:191], v[80:81], v[206:207]
	v_pk_fma_f32 v[208:209], v[192:193], v[82:83], v[208:209]
	v_mul_f32_e32 v210, 0xbfb8aa3b, v202
	v_mul_f32_e32 v211, 0xbfb8aa3b, v203
	v_mul_f32_e32 v212, 0xbfb8aa3b, v204
	v_mul_f32_e32 v213, 0xbfb8aa3b, v205
	v_mul_f32_e32 v214, 0xbfb8aa3b, v206
	v_mul_f32_e32 v215, 0xbfb8aa3b, v207
	v_mul_f32_e32 v216, 0xbfb8aa3b, v208
	v_mul_f32_e32 v217, 0xbfb8aa3b, v209
	v_exp_f32_e32 v210, v210
	v_exp_f32_e32 v211, v211
	v_exp_f32_e32 v212, v212
	v_exp_f32_e32 v213, v213
	v_exp_f32_e32 v214, v214
	v_exp_f32_e32 v215, v215
	v_exp_f32_e32 v216, v216
	v_exp_f32_e32 v217, v217
	v_add_f32_e32 v210, 1.0, v210
	v_add_f32_e32 v211, 1.0, v211
	v_add_f32_e32 v212, 1.0, v212
	v_add_f32_e32 v213, 1.0, v213
	v_add_f32_e32 v214, 1.0, v214
	v_add_f32_e32 v215, 1.0, v215
	v_add_f32_e32 v216, 1.0, v216
	v_add_f32_e32 v217, 1.0, v217
	v_rcp_f32_e32 v210, v210
	v_rcp_f32_e32 v211, v211
	v_rcp_f32_e32 v212, v212
	v_rcp_f32_e32 v213, v213
	v_rcp_f32_e32 v214, v214
	v_rcp_f32_e32 v215, v215
	v_rcp_f32_e32 v216, v216
	v_rcp_f32_e32 v217, v217
	v_pk_mul_f32 v[202:203], v[202:203], v[210:211]
	v_pk_mul_f32 v[204:205], v[204:205], v[212:213]
	v_pk_mul_f32 v[206:207], v[206:207], v[214:215]
	v_pk_mul_f32 v[208:209], v[208:209], v[216:217]
	v_cvt_pk_bf16_f32 v222, v202, v203
	v_cvt_pk_bf16_f32 v223, v204, v205
	v_cvt_pk_bf16_f32 v224, v206, v207
	v_cvt_pk_bf16_f32 v225, v208, v209
	global_store_dwordx4 v238, v[222:225], s[62:63] offset:1024 sc0 sc1
	v_pk_fma_f32 v[202:203], v[162:163], v[60:61], v[194:195]
	v_pk_fma_f32 v[204:205], v[164:165], v[62:63], v[196:197]
	v_pk_fma_f32 v[206:207], v[166:167], v[64:65], v[198:199]
	v_pk_fma_f32 v[208:209], v[168:169], v[66:67], v[200:201]
	v_pk_fma_f32 v[202:203], v[170:171], v[68:69], v[202:203]
; __device__ __forceinline__ unsigned cvt_pk(float lo, float hi) { f32x2 v = {lo, hi}; bf16x2_t b = __builtin_convertvector(v, bf16x2_t); return __builtin_bit_cast(unsigned, b); }
; __device__ __forceinline__ float bflo(unsigned w) { return __uint_as_float(w << 16); }
; __device__ __forceinline__ float bfhi(unsigned w) { return __uint_as_float(w & 0xffff0000u); }
; __device__ __forceinline__ float silu_f(float x) { return x * __builtin_amdgcn_rcpf(1.f + __builtin_amdgcn_exp2f(-1.4426950409f * x)); }
; __device__ __forceinline__ void ssd_prompt_item(const Params& p, int item, const int wv) {
;     ...
;       for (int jj = 0; jj < 8; ++jj) {
;         float o[8];
; #pragma unroll
;         for (int e = 0; e < 8; ++e) o[e] = bias[e];
; #pragma unroll
;         for (int k = 0; k < 4; ++k) {
;           u32x4 uu = u[jj + k];
;           o[0] += w[k][0] * bflo(uu.x); o[1] += w[k][1] * bfhi(uu.x); o[2] += w[k][2] * bflo(uu.y); o[3] += w[k][3] * bfhi(uu.y);
;           o[4] += w[k][4] * bflo(uu.z); o[5] += w[k][5] * bfhi(uu.z); o[6] += w[k][6] * bflo(uu.w); o[7] += w[k][7] * bfhi(uu.w);
;         }
; #pragma unroll
;         for (int e = 0; e < 8; ++e) o[e] = silu_f(o[e]);
; #pragma unroll
;         for (int e2 = 0; e2 < 4; ++e2) outp[jj][e2] = cvt_pk(o[2 * e2], o[2 * e2 + 1]);
;       }
	v_pk_fma_f32 v[204:205], v[172:173], v[70:71], v[204:205]
	v_pk_fma_f32 v[206:207], v[174:175], v[72:73], v[206:207]
	v_pk_fma_f32 v[208:209], v[176:177], v[74:75], v[208:209]
	v_pk_fma_f32 v[202:203], v[178:179], v[76:77], v[202:203]
	v_pk_fma_f32 v[204:205], v[180:181], v[78:79], v[204:205]
	v_pk_fma_f32 v[206:207], v[182:183], v[80:81], v[206:207]
	v_pk_fma_f32 v[208:209], v[184:185], v[82:83], v[208:209]
	v_pk_fma_f32 v[202:203], v[186:187], v[84:85], v[202:203]
	v_pk_fma_f32 v[204:205], v[188:189], v[86:87], v[204:205]
	v_pk_fma_f32 v[206:207], v[190:191], v[88:89], v[206:207]
	v_pk_fma_f32 v[208:209], v[192:193], v[90:91], v[208:209]
	v_mul_f32_e32 v210, 0xbfb8aa3b, v202
	v_mul_f32_e32 v211, 0xbfb8aa3b, v203
	v_mul_f32_e32 v212, 0xbfb8aa3b, v204
	v_mul_f32_e32 v213, 0xbfb8aa3b, v205
	v_mul_f32_e32 v214, 0xbfb8aa3b, v206
	v_mul_f32_e32 v215, 0xbfb8aa3b, v207
	v_mul_f32_e32 v216, 0xbfb8aa3b, v208
	v_mul_f32_e32 v217, 0xbfb8aa3b, v209
	v_exp_f32_e32 v210, v210
	v_exp_f32_e32 v211, v211
	v_exp_f32_e32 v212, v212
	v_exp_f32_e32 v213, v213
	v_exp_f32_e32 v214, v214
	v_exp_f32_e32 v215, v215
	v_exp_f32_e32 v216, v216
	v_exp_f32_e32 v217, v217
	v_add_f32_e32 v210, 1.0, v210
	v_add_f32_e32 v211, 1.0, v211
	v_add_f32_e32 v212, 1.0, v212
	v_add_f32_e32 v213, 1.0, v213
	v_add_f32_e32 v214, 1.0, v214
	v_add_f32_e32 v215, 1.0, v215
	v_add_f32_e32 v216, 1.0, v216
	v_add_f32_e32 v217, 1.0, v217
	v_rcp_f32_e32 v210, v210
	v_rcp_f32_e32 v211, v211
	v_rcp_f32_e32 v212, v212
	v_rcp_f32_e32 v213, v213
	v_rcp_f32_e32 v214, v214
	v_rcp_f32_e32 v215, v215
	v_rcp_f32_e32 v216, v216
	v_rcp_f32_e32 v217, v217
	v_pk_mul_f32 v[202:203], v[202:203], v[210:211]
	v_pk_mul_f32 v[204:205], v[204:205], v[212:213]
	v_pk_mul_f32 v[206:207], v[206:207], v[214:215]
	v_pk_mul_f32 v[208:209], v[208:209], v[216:217]
	v_cvt_pk_bf16_f32 v218, v202, v203
	v_cvt_pk_bf16_f32 v219, v204, v205
	v_cvt_pk_bf16_f32 v220, v206, v207
	v_cvt_pk_bf16_f32 v221, v208, v209
	global_store_dwordx4 v238, v[218:221], s[62:63] offset:2048 sc0 sc1
	v_pk_fma_f32 v[202:203], v[162:163], v[68:69], v[194:195]
	v_pk_fma_f32 v[204:205], v[164:165], v[70:71], v[196:197]
	v_pk_fma_f32 v[206:207], v[166:167], v[72:73], v[198:199]
	v_pk_fma_f32 v[208:209], v[168:169], v[74:75], v[200:201]
	v_pk_fma_f32 v[202:203], v[170:171], v[76:77], v[202:203]
	v_pk_fma_f32 v[204:205], v[172:173], v[78:79], v[204:205]
	v_pk_fma_f32 v[206:207], v[174:175], v[80:81], v[206:207]
	v_pk_fma_f32 v[208:209], v[176:177], v[82:83], v[208:209]
	v_pk_fma_f32 v[202:203], v[178:179], v[84:85], v[202:203]
	v_pk_fma_f32 v[204:205], v[180:181], v[86:87], v[204:205]
	v_pk_fma_f32 v[206:207], v[182:183], v[88:89], v[206:207]
	v_pk_fma_f32 v[208:209], v[184:185], v[90:91], v[208:209]
	v_pk_fma_f32 v[202:203], v[186:187], v[92:93], v[202:203]
	v_pk_fma_f32 v[204:205], v[188:189], v[94:95], v[204:205]
	v_pk_fma_f32 v[206:207], v[190:191], v[96:97], v[206:207]
	v_pk_fma_f32 v[208:209], v[192:193], v[98:99], v[208:209]
	v_mul_f32_e32 v210, 0xbfb8aa3b, v202
	v_mul_f32_e32 v211, 0xbfb8aa3b, v203
	v_mul_f32_e32 v212, 0xbfb8aa3b, v204
	v_mul_f32_e32 v213, 0xbfb8aa3b, v205
	v_mul_f32_e32 v214, 0xbfb8aa3b, v206
	v_mul_f32_e32 v215, 0xbfb8aa3b, v207
	v_mul_f32_e32 v216, 0xbfb8aa3b, v208
	v_mul_f32_e32 v217, 0xbfb8aa3b, v209
	v_exp_f32_e32 v210, v210
	v_exp_f32_e32 v211, v211
	v_exp_f32_e32 v212, v212
	v_exp_f32_e32 v213, v213
	v_exp_f32_e32 v214, v214
	v_exp_f32_e32 v215, v215
	v_exp_f32_e32 v216, v216
	v_exp_f32_e32 v217, v217
	v_add_f32_e32 v210, 1.0, v210
	v_add_f32_e32 v211, 1.0, v211
	v_add_f32_e32 v212, 1.0, v212
	v_add_f32_e32 v213, 1.0, v213
	v_add_f32_e32 v214, 1.0, v214
	v_add_f32_e32 v215, 1.0, v215
	v_add_f32_e32 v216, 1.0, v216
	v_add_f32_e32 v217, 1.0, v217
	v_rcp_f32_e32 v210, v210
	v_rcp_f32_e32 v211, v211
	v_rcp_f32_e32 v212, v212
	v_rcp_f32_e32 v213, v213
	v_rcp_f32_e32 v214, v214
	v_rcp_f32_e32 v215, v215
	v_rcp_f32_e32 v216, v216
	v_rcp_f32_e32 v217, v217
	v_pk_mul_f32 v[202:203], v[202:203], v[210:211]
	v_pk_mul_f32 v[204:205], v[204:205], v[212:213]
	v_pk_mul_f32 v[206:207], v[206:207], v[214:215]
	v_pk_mul_f32 v[208:209], v[208:209], v[216:217]
	v_cvt_pk_bf16_f32 v222, v202, v203
	v_cvt_pk_bf16_f32 v223, v204, v205
	v_cvt_pk_bf16_f32 v224, v206, v207
	v_cvt_pk_bf16_f32 v225, v208, v209
	global_store_dwordx4 v238, v[222:225], s[62:63] offset:3072 sc0 sc1
	v_pk_fma_f32 v[202:203], v[162:163], v[76:77], v[194:195]
	v_pk_fma_f32 v[204:205], v[164:165], v[78:79], v[196:197]
	v_pk_fma_f32 v[206:207], v[166:167], v[80:81], v[198:199]
	v_pk_fma_f32 v[208:209], v[168:169], v[82:83], v[200:201]
	v_pk_fma_f32 v[202:203], v[170:171], v[84:85], v[202:203]
	v_pk_fma_f32 v[204:205], v[172:173], v[86:87], v[204:205]
	v_pk_fma_f32 v[206:207], v[174:175], v[88:89], v[206:207]
	v_pk_fma_f32 v[208:209], v[176:177], v[90:91], v[208:209]
	v_pk_fma_f32 v[202:203], v[178:179], v[92:93], v[202:203]
	v_pk_fma_f32 v[204:205], v[180:181], v[94:95], v[204:205]
	v_pk_fma_f32 v[206:207], v[182:183], v[96:97], v[206:207]
	v_pk_fma_f32 v[208:209], v[184:185], v[98:99], v[208:209]
	v_pk_fma_f32 v[202:203], v[186:187], v[100:101], v[202:203]
	v_pk_fma_f32 v[204:205], v[188:189], v[102:103], v[204:205]
	v_pk_fma_f32 v[206:207], v[190:191], v[104:105], v[206:207]
	v_pk_fma_f32 v[208:209], v[192:193], v[106:107], v[208:209]
	v_mul_f32_e32 v210, 0xbfb8aa3b, v202
	v_mul_f32_e32 v211, 0xbfb8aa3b, v203
	v_mul_f32_e32 v212, 0xbfb8aa3b, v204
	v_mul_f32_e32 v213, 0xbfb8aa3b, v205
	v_mul_f32_e32 v214, 0xbfb8aa3b, v206
	v_mul_f32_e32 v215, 0xbfb8aa3b, v207
	v_mul_f32_e32 v216, 0xbfb8aa3b, v208
	v_mul_f32_e32 v217, 0xbfb8aa3b, v209
	v_exp_f32_e32 v210, v210
; __device__ __forceinline__ unsigned cvt_pk(float lo, float hi) { f32x2 v = {lo, hi}; bf16x2_t b = __builtin_convertvector(v, bf16x2_t); return __builtin_bit_cast(unsigned, b); }
; __device__ __forceinline__ float bflo(unsigned w) { return __uint_as_float(w << 16); }
; __device__ __forceinline__ float bfhi(unsigned w) { return __uint_as_float(w & 0xffff0000u); }
; __device__ __forceinline__ float silu_f(float x) { return x * __builtin_amdgcn_rcpf(1.f + __builtin_amdgcn_exp2f(-1.4426950409f * x)); }
; __device__ __forceinline__ void ssd_prompt_item(const Params& p, int item, const int wv) {
;     ...
;       for (int jj = 0; jj < 8; ++jj) {
;         float o[8];
; #pragma unroll
;         for (int e = 0; e < 8; ++e) o[e] = bias[e];
; #pragma unroll
;         for (int k = 0; k < 4; ++k) {
;           u32x4 uu = u[jj + k];
;           o[0] += w[k][0] * bflo(uu.x); o[1] += w[k][1] * bfhi(uu.x); o[2] += w[k][2] * bflo(uu.y); o[3] += w[k][3] * bfhi(uu.y);
;           o[4] += w[k][4] * bflo(uu.z); o[5] += w[k][5] * bfhi(uu.z); o[6] += w[k][6] * bflo(uu.w); o[7] += w[k][7] * bfhi(uu.w);
;         }
; #pragma unroll
;         for (int e = 0; e < 8; ++e) o[e] = silu_f(o[e]);
; #pragma unroll
;         for (int e2 = 0; e2 < 4; ++e2) outp[jj][e2] = cvt_pk(o[2 * e2], o[2 * e2 + 1]);
;       }
	v_exp_f32_e32 v211, v211
	v_exp_f32_e32 v212, v212
	v_exp_f32_e32 v213, v213
	v_exp_f32_e32 v214, v214
	v_exp_f32_e32 v215, v215
	v_exp_f32_e32 v216, v216
	v_exp_f32_e32 v217, v217
	v_add_f32_e32 v210, 1.0, v210
	v_add_f32_e32 v211, 1.0, v211
	v_add_f32_e32 v212, 1.0, v212
	v_add_f32_e32 v213, 1.0, v213
	v_add_f32_e32 v214, 1.0, v214
	v_add_f32_e32 v215, 1.0, v215
	v_add_f32_e32 v216, 1.0, v216
	v_add_f32_e32 v217, 1.0, v217
	v_rcp_f32_e32 v210, v210
	v_rcp_f32_e32 v211, v211
	v_rcp_f32_e32 v212, v212
	v_rcp_f32_e32 v213, v213
	v_rcp_f32_e32 v214, v214
	v_rcp_f32_e32 v215, v215
	v_rcp_f32_e32 v216, v216
	v_rcp_f32_e32 v217, v217
	v_pk_mul_f32 v[202:203], v[202:203], v[210:211]
	v_pk_mul_f32 v[204:205], v[204:205], v[212:213]
	v_pk_mul_f32 v[206:207], v[206:207], v[214:215]
	v_pk_mul_f32 v[208:209], v[208:209], v[216:217]
	v_cvt_pk_bf16_f32 v218, v202, v203
	v_cvt_pk_bf16_f32 v219, v204, v205
	v_cvt_pk_bf16_f32 v220, v206, v207
	v_cvt_pk_bf16_f32 v221, v208, v209
	global_store_dwordx4 v239, v[218:221], s[62:63] sc0 sc1
	v_pk_fma_f32 v[202:203], v[162:163], v[84:85], v[194:195]
	v_pk_fma_f32 v[204:205], v[164:165], v[86:87], v[196:197]
	v_pk_fma_f32 v[206:207], v[166:167], v[88:89], v[198:199]
	v_pk_fma_f32 v[208:209], v[168:169], v[90:91], v[200:201]
	v_pk_fma_f32 v[202:203], v[170:171], v[92:93], v[202:203]
	v_pk_fma_f32 v[204:205], v[172:173], v[94:95], v[204:205]
	v_pk_fma_f32 v[206:207], v[174:175], v[96:97], v[206:207]
	v_pk_fma_f32 v[208:209], v[176:177], v[98:99], v[208:209]
	v_pk_fma_f32 v[202:203], v[178:179], v[100:101], v[202:203]
	v_pk_fma_f32 v[204:205], v[180:181], v[102:103], v[204:205]
	v_pk_fma_f32 v[206:207], v[182:183], v[104:105], v[206:207]
	v_pk_fma_f32 v[208:209], v[184:185], v[106:107], v[208:209]
	v_pk_fma_f32 v[202:203], v[186:187], v[108:109], v[202:203]
	v_pk_fma_f32 v[204:205], v[188:189], v[110:111], v[204:205]
	v_pk_fma_f32 v[206:207], v[190:191], v[112:113], v[206:207]
	v_pk_fma_f32 v[208:209], v[192:193], v[114:115], v[208:209]
	v_mul_f32_e32 v210, 0xbfb8aa3b, v202
	v_mul_f32_e32 v211, 0xbfb8aa3b, v203
	v_mul_f32_e32 v212, 0xbfb8aa3b, v204
	v_mul_f32_e32 v213, 0xbfb8aa3b, v205
	v_mul_f32_e32 v214, 0xbfb8aa3b, v206
	v_mul_f32_e32 v215, 0xbfb8aa3b, v207
	v_mul_f32_e32 v216, 0xbfb8aa3b, v208
	v_mul_f32_e32 v217, 0xbfb8aa3b, v209
	v_exp_f32_e32 v210, v210
	v_exp_f32_e32 v211, v211
	v_exp_f32_e32 v212, v212
	v_exp_f32_e32 v213, v213
	v_exp_f32_e32 v214, v214
	v_exp_f32_e32 v215, v215
	v_exp_f32_e32 v216, v216
	v_exp_f32_e32 v217, v217
	v_add_f32_e32 v210, 1.0, v210
	v_add_f32_e32 v211, 1.0, v211
	v_add_f32_e32 v212, 1.0, v212
	v_add_f32_e32 v213, 1.0, v213
	v_add_f32_e32 v214, 1.0, v214
	v_add_f32_e32 v215, 1.0, v215
	v_add_f32_e32 v216, 1.0, v216
	v_add_f32_e32 v217, 1.0, v217
	v_rcp_f32_e32 v210, v210
	v_rcp_f32_e32 v211, v211
	v_rcp_f32_e32 v212, v212
	v_rcp_f32_e32 v213, v213
	v_rcp_f32_e32 v214, v214
	v_rcp_f32_e32 v215, v215
	v_rcp_f32_e32 v216, v216
	v_rcp_f32_e32 v217, v217
	v_pk_mul_f32 v[202:203], v[202:203], v[210:211]
	v_pk_mul_f32 v[204:205], v[204:205], v[212:213]
	v_pk_mul_f32 v[206:207], v[206:207], v[214:215]
	v_pk_mul_f32 v[208:209], v[208:209], v[216:217]
	v_cvt_pk_bf16_f32 v222, v202, v203
	v_cvt_pk_bf16_f32 v223, v204, v205
	v_cvt_pk_bf16_f32 v224, v206, v207
	v_cvt_pk_bf16_f32 v225, v208, v209
	global_store_dwordx4 v239, v[222:225], s[62:63] offset:1024 sc0 sc1
	v_pk_fma_f32 v[202:203], v[162:163], v[92:93], v[194:195]
	v_pk_fma_f32 v[204:205], v[164:165], v[94:95], v[196:197]
	v_pk_fma_f32 v[206:207], v[166:167], v[96:97], v[198:199]
	v_pk_fma_f32 v[208:209], v[168:169], v[98:99], v[200:201]
	v_pk_fma_f32 v[202:203], v[170:171], v[100:101], v[202:203]
	v_pk_fma_f32 v[204:205], v[172:173], v[102:103], v[204:205]
	v_pk_fma_f32 v[206:207], v[174:175], v[104:105], v[206:207]
	v_pk_fma_f32 v[208:209], v[176:177], v[106:107], v[208:209]
	v_pk_fma_f32 v[202:203], v[178:179], v[108:109], v[202:203]
	v_pk_fma_f32 v[204:205], v[180:181], v[110:111], v[204:205]
	v_pk_fma_f32 v[206:207], v[182:183], v[112:113], v[206:207]
	v_pk_fma_f32 v[208:209], v[184:185], v[114:115], v[208:209]
	v_pk_fma_f32 v[202:203], v[186:187], v[116:117], v[202:203]
	v_pk_fma_f32 v[204:205], v[188:189], v[118:119], v[204:205]
	v_pk_fma_f32 v[206:207], v[190:191], v[120:121], v[206:207]
	v_pk_fma_f32 v[208:209], v[192:193], v[122:123], v[208:209]
	v_mul_f32_e32 v210, 0xbfb8aa3b, v202
	v_mul_f32_e32 v211, 0xbfb8aa3b, v203
	v_mul_f32_e32 v212, 0xbfb8aa3b, v204
	v_mul_f32_e32 v213, 0xbfb8aa3b, v205
	v_mul_f32_e32 v214, 0xbfb8aa3b, v206
	v_mul_f32_e32 v215, 0xbfb8aa3b, v207
	v_mul_f32_e32 v216, 0xbfb8aa3b, v208
	v_mul_f32_e32 v217, 0xbfb8aa3b, v209
	v_exp_f32_e32 v210, v210
	v_exp_f32_e32 v211, v211
	v_exp_f32_e32 v212, v212
	v_exp_f32_e32 v213, v213
	v_exp_f32_e32 v214, v214
	v_exp_f32_e32 v215, v215
	v_exp_f32_e32 v216, v216
	v_exp_f32_e32 v217, v217
	v_add_f32_e32 v210, 1.0, v210
	v_add_f32_e32 v211, 1.0, v211
	v_add_f32_e32 v212, 1.0, v212
	v_add_f32_e32 v213, 1.0, v213
	v_add_f32_e32 v214, 1.0, v214
	v_add_f32_e32 v215, 1.0, v215
	v_add_f32_e32 v216, 1.0, v216
	v_add_f32_e32 v217, 1.0, v217
	v_rcp_f32_e32 v210, v210
	v_rcp_f32_e32 v211, v211
	v_rcp_f32_e32 v212, v212
	v_rcp_f32_e32 v213, v213
	v_rcp_f32_e32 v214, v214
	v_rcp_f32_e32 v215, v215
	v_rcp_f32_e32 v216, v216
	v_rcp_f32_e32 v217, v217
	v_pk_mul_f32 v[202:203], v[202:203], v[210:211]
	v_pk_mul_f32 v[204:205], v[204:205], v[212:213]
	v_pk_mul_f32 v[206:207], v[206:207], v[214:215]
	v_pk_mul_f32 v[208:209], v[208:209], v[216:217]
	v_cvt_pk_bf16_f32 v218, v202, v203
	v_cvt_pk_bf16_f32 v219, v204, v205
	v_cvt_pk_bf16_f32 v220, v206, v207
	v_cvt_pk_bf16_f32 v221, v208, v209
; __device__ __forceinline__ unsigned xb_ld(unsigned* p) { return __hip_atomic_load(p, __ATOMIC_RELAXED, __HIP_MEMORY_SCOPE_AGENT); }
; #define XB_SPIN(cond, bar) do { unsigned _sp = 0; while (cond) { __builtin_amdgcn_s_sleep(1); \
;     if ((++_sp & 255u) == 0u) { if (xb_ld(&(bar)[XB_TMO])) break; if (_sp > XB_SPIN_CAP) { atomicAdd(&(bar)[XB_TMO], 1u); break; } } } } while (0)
; __device__ __forceinline__ void ssd_prompt_item(const Params& p, int item, const int wv) {
;     ...
;   const float Ah = -__expf(p.in[16][h]);
;   const float Dh = p.in[17][h];
;   const float* convw = p.in[13];
;   const float* convb = p.in[14];
;   const int cc = tid & 31, rg = tid >> 5;
;   const int colbc = (cc < 16) ? (1024 + g * 128 + cc * 8) : (1280 + g * 128 + (cc - 16) * 8);
;   const int xc = tid & 7, xr = tid >> 3;
;   const int colx = h * 64 + xc * 8;
;   const int j0 = rg * 8;
;   f32x4 hacc[4];
; #pragma unroll
;   for (int pb = 0; pb < 4; ++pb) hacc[pb] = (f32x4){0.f, 0.f, 0.f, 0.f};
;   u32x4 u[11], ux[5];
;   float a0 = 0.f, a1 = 0.f;
; __device__ __forceinline__ void attn_prompt_item(const Params& p, int item, const int wv, unsigned* bar) {
;     ...
;   if (wv == 0) { if (lane == 0) { XB_SPIN(xb_ld(&bar[6144 + (b * 4 + h) * 16]) == 0u, bar); } }
;   __syncthreads();
;   __builtin_amdgcn_fence(__ATOMIC_ACQUIRE, "agent");
	global_store_dwordx4 v239, v[218:221], s[62:63] offset:2048 sc0 sc1
	v_pk_fma_f32 v[202:203], v[162:163], v[100:101], v[194:195]
	v_pk_fma_f32 v[204:205], v[164:165], v[102:103], v[196:197]
	v_pk_fma_f32 v[206:207], v[166:167], v[104:105], v[198:199]
	v_pk_fma_f32 v[208:209], v[168:169], v[106:107], v[200:201]
	v_pk_fma_f32 v[202:203], v[170:171], v[108:109], v[202:203]
	v_pk_fma_f32 v[204:205], v[172:173], v[110:111], v[204:205]
	v_pk_fma_f32 v[206:207], v[174:175], v[112:113], v[206:207]
	v_pk_fma_f32 v[208:209], v[176:177], v[114:115], v[208:209]
	v_pk_fma_f32 v[202:203], v[178:179], v[116:117], v[202:203]
	v_pk_fma_f32 v[204:205], v[180:181], v[118:119], v[204:205]
	v_pk_fma_f32 v[206:207], v[182:183], v[120:121], v[206:207]
	v_pk_fma_f32 v[208:209], v[184:185], v[122:123], v[208:209]
	v_pk_fma_f32 v[202:203], v[186:187], v[124:125], v[202:203]
	v_pk_fma_f32 v[204:205], v[188:189], v[126:127], v[204:205]
	v_pk_fma_f32 v[206:207], v[190:191], v[128:129], v[206:207]
	v_pk_fma_f32 v[208:209], v[192:193], v[130:131], v[208:209]
	v_mul_f32_e32 v210, 0xbfb8aa3b, v202
	v_mul_f32_e32 v211, 0xbfb8aa3b, v203
	v_mul_f32_e32 v212, 0xbfb8aa3b, v204
	v_mul_f32_e32 v213, 0xbfb8aa3b, v205
	v_mul_f32_e32 v214, 0xbfb8aa3b, v206
	v_mul_f32_e32 v215, 0xbfb8aa3b, v207
	v_mul_f32_e32 v216, 0xbfb8aa3b, v208
	v_mul_f32_e32 v217, 0xbfb8aa3b, v209
	v_exp_f32_e32 v210, v210
	v_exp_f32_e32 v211, v211
	v_exp_f32_e32 v212, v212
	v_exp_f32_e32 v213, v213
	v_exp_f32_e32 v214, v214
	v_exp_f32_e32 v215, v215
	v_exp_f32_e32 v216, v216
	v_exp_f32_e32 v217, v217
	v_add_f32_e32 v210, 1.0, v210
	v_add_f32_e32 v211, 1.0, v211
	v_add_f32_e32 v212, 1.0, v212
	v_add_f32_e32 v213, 1.0, v213
	v_add_f32_e32 v214, 1.0, v214
	v_add_f32_e32 v215, 1.0, v215
	v_add_f32_e32 v216, 1.0, v216
	v_add_f32_e32 v217, 1.0, v217
	v_rcp_f32_e32 v210, v210
	v_rcp_f32_e32 v211, v211
	v_rcp_f32_e32 v212, v212
	v_rcp_f32_e32 v213, v213
	v_rcp_f32_e32 v214, v214
	v_rcp_f32_e32 v215, v215
	v_rcp_f32_e32 v216, v216
	v_rcp_f32_e32 v217, v217
	v_pk_mul_f32 v[202:203], v[202:203], v[210:211]
	v_pk_mul_f32 v[204:205], v[204:205], v[212:213]
	v_pk_mul_f32 v[206:207], v[206:207], v[214:215]
	v_pk_mul_f32 v[208:209], v[208:209], v[216:217]
	v_cvt_pk_bf16_f32 v222, v202, v203
	v_cvt_pk_bf16_f32 v223, v204, v205
	v_cvt_pk_bf16_f32 v224, v206, v207
	v_cvt_pk_bf16_f32 v225, v208, v209
	global_store_dwordx4 v239, v[222:225], s[62:63] offset:3072 sc0 sc1
	s_and_b32 s6, s68, 15
	v_readlane_b32 s52, v251, 22
	s_lshl_b32 s18, s6, 2
	v_readlane_b32 s53, v251, 23
	v_mbcnt_lo_u32_b32 v71, -1, 0
	v_mbcnt_hi_u32_b32 v71, -1, v71
	v_mov_b32_e32 v0, s18
	v_readlane_b32 s54, v251, 24
	v_readlane_b32 s55, v251, 25
	s_mov_b64 s[8:9], s[52:53]
	v_and_b32_e32 v72, 31, v71
	s_lshl_b32 s0, s68, 4
	s_mov_b64 s[10:11], s[54:55]
	global_load_dword v69, v0, s[8:9]
	global_load_dword v144, v0, s[10:11]
	s_and_b32 s0, s0, 0x80
	v_lshlrev_b32_e32 v0, 3, v72
	s_waitcnt lgkmcnt(0)
	v_or_b32_e32 v1, s0, v0
	s_addk_i32 s0, 0x480
	v_or_b32_e32 v1, 0x400, v1
	v_add_u32_e32 v0, s0, v0
	v_cmp_gt_u32_e32 vcc, 16, v72
	v_lshlrev_b32_e32 v65, 3, v71
	v_add_u32_e32 v64, s82, v71
	v_cndmask_b32_e32 v75, v0, v1, vcc
	v_and_b32_e32 v67, 56, v65
	v_readlane_b32 s8, v250, 8
	v_ashrrev_i32_e32 v70, 3, v64
	v_ashrrev_i32_e32 v40, 2, v64
	v_lshlrev_b32_e32 v142, 1, v75
	v_readlane_b32 s9, v250, 9
	v_lshl_or_b32 v76, s6, 6, v67
	v_and_b32_e32 v66, -8, v40
	v_lshl_add_u64 v[146:147], s[8:9], 0, v[142:143]
	v_lshlrev_b32_e32 v68, 1, v70
	v_lshlrev_b32_e32 v142, 1, v76
	s_lshl_b32 s0, s68, 7
	v_add_u32_e32 v0, -3, v66
	v_cmp_lt_i32_e64 s[12:13], 7, v40
	v_add_u32_e32 v2, -2, v66
	v_add_u32_e32 v8, -1, v66
	v_cmp_lt_i32_e64 s[4:5], -1, v40
	v_or_b32_e32 v16, 1, v66
	v_or_b32_e32 v18, 2, v66
	v_or_b32_e32 v24, 3, v66
	v_or_b32_e32 v26, 4, v66
	v_or_b32_e32 v32, 5, v66
	v_or_b32_e32 v34, 6, v66
	v_or_b32_e32 v74, 7, v40
	v_add_u32_e32 v42, -3, v68
	v_lshl_add_u64 v[56:57], s[8:9], 0, v[142:143]
	v_cmp_lt_i32_e64 s[10:11], 1, v70
	v_add_u32_e32 v48, -2, v68
	v_cmp_lt_i32_e64 s[8:9], 0, v70
	v_add_u32_e32 v50, -1, v68
	v_cmp_lt_i32_e64 s[6:7], -1, v70
	v_or_b32_e32 v60, 1, v68
	s_and_b32 s41, s0, 0x3800
	v_cndmask_b32_e64 v0, 0, v0, s[12:13]
	v_cndmask_b32_e64 v2, 0, v2, s[12:13]
	v_cndmask_b32_e64 v8, 0, v8, s[12:13]
	v_cndmask_b32_e64 v10, 0, v66, s[4:5]
	v_cndmask_b32_e64 v16, 0, v16, s[4:5]
	v_cndmask_b32_e64 v18, 0, v18, s[4:5]
	v_cndmask_b32_e64 v24, 0, v24, s[4:5]
	v_cndmask_b32_e64 v26, 0, v26, s[4:5]
	v_cndmask_b32_e64 v32, 0, v32, s[4:5]
	v_cndmask_b32_e64 v34, 0, v34, s[4:5]
	v_cndmask_b32_e64 v40, 0, v74, s[4:5]
	v_cndmask_b32_e64 v42, 0, v42, s[10:11]
	v_cndmask_b32_e64 v48, 0, v48, s[8:9]
	v_cndmask_b32_e64 v50, 0, v50, s[8:9]
	v_cndmask_b32_e64 v58, 0, v68, s[6:7]
	v_cndmask_b32_e64 v60, 0, v60, s[6:7]
	v_add_u32_e32 v0, s41, v0
	v_add_u32_e32 v2, s41, v2
	v_add_u32_e32 v8, s41, v8
	v_add_u32_e32 v10, s41, v10
	v_add_u32_e32 v16, s41, v16
	v_add_u32_e32 v18, s41, v18
	v_add_u32_e32 v24, s41, v24
	v_add_u32_e32 v26, s41, v26
	v_add_u32_e32 v32, s41, v32
	v_add_u32_e32 v34, s41, v34
	v_add_u32_e32 v40, s41, v40
	v_add_u32_e32 v42, s41, v42
	v_add_u32_e32 v48, s41, v48
	v_add_u32_e32 v50, s41, v50
	v_add_u32_e32 v58, s41, v58
	v_add_u32_e32 v60, s41, v60
	v_mad_i64_i32 v[44:45], s[0:1], v42, s33, v[56:57]
	v_mad_i64_i32 v[48:49], s[0:1], v48, s33, v[56:57]
	v_mad_i64_i32 v[52:53], s[0:1], v50, s33, v[56:57]
	v_mad_i64_i32 v[58:59], s[0:1], v58, s33, v[56:57]
	v_mad_i64_i32 v[60:61], s[0:1], v60, s33, v[56:57]
	s_nop 0
	s_nop 0
	s_nop 0
	s_nop 0
	s_nop 0
	s_nop 0
	s_nop 0
	s_nop 0
	s_nop 0
	s_nop 0
	s_nop 0
	s_waitcnt vmcnt(0)
	s_barrier
	s_cmp_lg_u32 s82, 0
	s_cbranch_scc1 .Lssdp_wait_done
	s_mov_b64 exec, 1
	s_lshr_b32 s86, s68, 3
	s_and_b32 s86, s86, 0x1f
	s_lshl_b32 s86, s86, 6
	s_add_u32 s86, s86, 0x1241d000
	s_add_u32 s84, s50, s86
	s_addc_u32 s85, s51, 0
	v_mov_b32_e32 v244, 0
	v_mov_b32_e32 v245, 1
	global_atomic_add v244, v245, s[84:85]
	s_waitcnt vmcnt(0)
	s_mov_b32 s86, 0
.Lssdp_spin:
	global_load_dword v246, v244, s[84:85] sc1
	s_waitcnt vmcnt(0)
	v_readfirstlane_b32 s87, v246
	s_cmp_ge_u32 s87, 8
	s_cbranch_scc1 .Lssdp_spin_done
	s_sleep 1
	s_add_u32 s86, s86, 1
	s_cmp_lt_u32 s86, 0x400000
	s_cbranch_scc1 .Lssdp_spin

; __device__ __forceinline__ void ssd_prompt_item(const Params& p, int item, const int wv) {
;     ...
;   SSD_PREFETCH(0);
.Lssdp_wait_done:
	s_barrier
	buffer_inv sc1
	s_waitcnt vmcnt(0)
	v_mov_b32_e32 v244, v242
	v_mov_b32_e32 v245, v243
	v_mov_b32_e32 v248, 0x1000
	s_nop 0
	v_lshl_add_u64 v[246:247], v[248:249], 0, v[244:245]
	global_load_dwordx4 v[0:3], v[244:245], off
	global_load_dwordx4 v[4:7], v[244:245], off offset:1024
	global_load_dwordx4 v[8:11], v[244:245], off offset:2048
	global_load_dwordx4 v[12:15], v[244:245], off offset:3072
	global_load_dwordx4 v[16:19], v[246:247], off
	global_load_dwordx4 v[20:23], v[246:247], off offset:1024
	global_load_dwordx4 v[24:27], v[246:247], off offset:2048
	global_load_dwordx4 v[28:31], v[246:247], off offset:3072
	global_load_dwordx4 v[44:47], v[44:45], off
	s_nop 0
	global_load_dwordx4 v[48:51], v[48:49], off
	s_nop 0
	global_load_dwordx4 v[52:55], v[52:53], off
	s_nop 0
	global_load_dwordx4 v[56:59], v[58:59], off
	s_nop 0
	global_load_dwordx4 v[60:63], v[60:61], off
	v_readlane_b32 s56, v251, 26
	v_readlane_b32 s57, v251, 27
	v_readlane_b32 s58, v251, 28
	v_readlane_b32 s59, v251, 29
	v_readlane_b32 s60, v251, 30
	v_readlane_b32 s61, v251, 31
	v_readlane_b32 s62, v251, 32
	v_readlane_b32 s63, v251, 33
	v_readlane_b32 s64, v251, 34
	v_readlane_b32 s65, v251, 35
	v_readlane_b32 s66, v251, 36
	v_readlane_b32 s67, v251, 37
	v_readlane_b32 s20, v251, 58
	v_readlane_b32 s52, v251, 38
	v_readlane_b32 s21, v251, 59
	v_readlane_b32 s62, v251, 48
	v_readlane_b32 s63, v251, 49
	v_readlane_b32 s64, v251, 50
	v_readlane_b32 s65, v251, 51
	v_cmp_lt_u32_e64 s[0:1], 15, v72
	v_lshlrev_b32_e32 v73, 1, v71
	s_and_b64 vcc, exec, s[20:21]
	v_mov_b32_e32 v148, v143
	v_mov_b32_e32 v149, v143
	s_mov_b64 s[22:23], s[62:63]
	s_mov_b64 s[24:25], s[64:65]
	v_readlane_b32 s53, v251, 39
	v_readlane_b32 s54, v251, 40
	v_readlane_b32 s55, v251, 41
	v_readlane_b32 s56, v251, 42
	v_readlane_b32 s57, v251, 43
	v_readlane_b32 s58, v251, 44
	v_readlane_b32 s59, v251, 45
	v_readlane_b32 s60, v251, 46
	v_readlane_b32 s61, v251, 47
	v_readlane_b32 s66, v251, 52
	v_readlane_b32 s67, v251, 53
	s_cbranch_vccnz .LBB0_568
	v_add_u32_e32 v78, s41, v73
	v_ashrrev_i32_e32 v79, 31, v78
	v_lshlrev_b64 v[80:81], 6, v[78:79]
	v_or_b32_e32 v78, 1, v78
	v_readlane_b32 s42, v250, 10
	v_readlane_b32 s20, v250, 20
	v_ashrrev_i32_e32 v79, 31, v78
	v_readlane_b32 s43, v250, 11
	v_readlane_b32 s21, v250, 21
	v_lshlrev_b64 v[78:79], 6, v[78:79]
	v_lshl_add_u64 v[80:81], s[42:43], 0, v[80:81]
	s_mov_b32 s19, s21
	v_lshl_add_u64 v[78:79], s[42:43], 0, v[78:79]
	v_lshl_add_u64 v[80:81], v[80:81], 0, s[18:19]
	v_lshl_add_u64 v[78:79], v[78:79], 0, s[18:19]
	global_load_dword v148, v[80:81], off
	global_load_dword v149, v[78:79], off

; __device__ __forceinline__ f32x4 unpack4(u32x2 w) { return (f32x4){bflo(w.x), bfhi(w.x), bflo(w.y), bfhi(w.y)}; }
; __device__ __forceinline__ int lane_fresh() { int l; asm volatile("v_mbcnt_lo_u32_b32 %0, -1, 0\n\tv_mbcnt_hi_u32_b32 %0, -1, %0" : "=v"(l)); return l; }
; #define MFMA16(a, b, c) __builtin_amdgcn_mfma_f32_16x16x32_bf16((a), (b), (c), 0, 0, 0)
; template <int NT, class FA, class FB, class FL>
; __device__ __forceinline__ void skgemm(FA aptr, FB bptr, FL ldf, const int KS, const int wv) {
;     ...
;   for (int i = 0; i < NT; ++i) {
;     f32x4 acc = {0.f, 0.f, 0.f, 0.f};
;     const int ld = ldf(i);
;     const u16* ap = aptr(i) + (size_t)fr * ld + wv * KS + fq * 8;
;     const u16* bp = bptr(i) + (size_t)fr * ld + wv * KS + fq * 8;
; #pragma unroll 8
;     for (int k = 0; k < KS; k += 32) acc = MFMA16(*(const bf16x8*)(bp + k), *(const bf16x8*)(ap + k), acc);
;     *(f32x4*)(part + ((i * 8 + wv) * 64 + lane) * 4) = acc;
;   }
;   __syncthreads();
; }
; __device__ __forceinline__ f32x4 skreduce(int i) {
;   const float* part = (const float*)g_shm;
;   const int lane = lane_fresh();
;   f32x4 s = {0.f, 0.f, 0.f, 0.f};
; #pragma unroll
;   for (int w = 0; w < 8; ++w) s += *(const f32x4*)(part + ((i * 8 + w) * 64 + lane) * 4);
; __device__ __forceinline__ void phaseG(const Params& p, const int wv, const int rep, unsigned* bar, const bool fused) {
;     ...
;   for (int gb = blockIdx.x; gb < 256; gb += gridDim.x) {
;     const int task0 = gb * 2, mt = task0 >> 6, nt0 = task0 & 63;
;     const u16* Ab = ACT + (size_t)(TP + mt * 16) * 4096;
;     skgemm<2>([&](int) { return Ab; }, [&](int i) { return WDN + (size_t)((nt0 + i) * 16) * 4096; }, [&](int) { return 4096; }, 512, wv);
;     if (!fused) {
;       if (wv < 2) {
;         const int lane_e = lane_fresh(), fr = lane_e & 15, fq = lane_e >> 4;
;         const int row = TP + mt * 16 + fr, col = (nt0 + wv) * 16 + fq * 4;
;         const size_t o = (size_t)row * 1024 + col;
;         *(f32x4*)(p.out + O_Y + o) = skreduce(wv) + unpack4(*(const u32x2*)(H2 + o));
;       }
.LBB0_1186:
	global_load_dwordx4 v[10:13], v[8:9], off offset:-256
	global_load_dwordx4 v[16:19], v[8:9], off offset:-192
	global_load_dwordx4 v[20:23], v[6:7], off offset:-256
	global_load_dwordx4 v[24:27], v[6:7], off offset:-192
	global_load_dwordx4 v[28:31], v[8:9], off offset:-128
	global_load_dwordx4 v[32:35], v[6:7], off offset:-128
	global_load_dwordx4 v[36:39], v[8:9], off offset:-64
	global_load_dwordx4 v[40:43], v[6:7], off offset:-64
	s_addk_i32 s2, 0x100
	s_cmpk_gt_u32 s2, 0x1df
	s_waitcnt vmcnt(5)
	v_mfma_f32_16x16x32_bf16 v[0:3], v[10:13], v[20:23], v[0:3]
	global_load_dwordx4 v[10:13], v[8:9], off
	global_load_dwordx4 v[20:23], v[6:7], off
	s_waitcnt vmcnt(6)
	v_mfma_f32_16x16x32_bf16 v[0:3], v[16:19], v[24:27], v[0:3]
	global_load_dwordx4 v[16:19], v[8:9], off offset:64
	global_load_dwordx4 v[24:27], v[6:7], off offset:64
	s_waitcnt vmcnt(6)
	v_mfma_f32_16x16x32_bf16 v[0:3], v[28:31], v[32:35], v[0:3]
	global_load_dwordx4 v[28:31], v[8:9], off offset:128
	global_load_dwordx4 v[32:35], v[6:7], off offset:128
	s_waitcnt vmcnt(6)
	v_mfma_f32_16x16x32_bf16 v[0:3], v[36:39], v[40:43], v[0:3]
	s_waitcnt vmcnt(4)
	v_mfma_f32_16x16x32_bf16 v[0:3], v[10:13], v[20:23], v[0:3]
	global_load_dwordx4 v[10:13], v[8:9], off offset:192
	v_lshl_add_u64 v[8:9], v[8:9], 0, s[16:17]
	s_waitcnt vmcnt(3)
	v_mfma_f32_16x16x32_bf16 v[0:3], v[16:19], v[24:27], v[0:3]
	global_load_dwordx4 v[16:19], v[6:7], off offset:192
	v_lshl_add_u64 v[6:7], v[6:7], 0, s[16:17]
	s_waitcnt vmcnt(2)
	v_mfma_f32_16x16x32_bf16 v[0:3], v[28:31], v[32:35], v[0:3]
	s_waitcnt vmcnt(0)
	v_mfma_f32_16x16x32_bf16 v[0:3], v[10:13], v[16:19], v[0:3]
	s_cbranch_scc0 .LBB0_1186
	s_lshl_b32 s2, s40, 1
	s_and_b32 s2, s2, 62
	s_and_b64 vcc, exec, s[0:1]
	s_mov_b64 s[24:25], -1
	s_nop 2
	ds_write_b128 v4, v[0:3] offset:8192
	s_waitcnt lgkmcnt(0)
	s_barrier
	s_cbranch_vccnz .LBB0_1191
	s_and_b64 vcc, exec, s[4:5]
	s_cbranch_vccnz .LBB0_1190
	v_mbcnt_lo_u32_b32 v1, -1, 0
	v_mbcnt_hi_u32_b32 v1, -1, v1
	s_or_b32 s19, s2, s41
	v_and_or_b32 v0, v1, 15, s20
	v_ashrrev_i32_e32 v1, 2, v1
	v_and_b32_e32 v1, -4, v1
	v_lshl_add_u32 v2, s19, 4, v1
	v_ashrrev_i32_e32 v1, 31, v0
	v_lshlrev_b64 v[0:1], 10, v[0:1]
	v_ashrrev_i32_e32 v3, 31, v2
	v_lshl_add_u64 v[36:37], v[0:1], 0, v[2:3]
	v_lshl_add_u64 v[0:1], v[36:37], 1, s[8:9]
	v_mbcnt_lo_u32_b32 v2, -1, 0
	v_mbcnt_hi_u32_b32 v2, -1, v2
	global_load_dwordx2 v[38:39], v[0:1], off
	v_lshl_add_u32 v4, v2, 4, s34
	ds_read_b128 v[0:3], v4
	ds_read_b128 v[6:9], v4 offset:1024
	ds_read_b128 v[10:13], v4 offset:2048
	ds_read_b128 v[16:19], v4 offset:3072
	ds_read_b128 v[20:23], v4 offset:4096
	ds_read_b128 v[24:27], v4 offset:5120
	ds_read_b128 v[28:31], v4 offset:6144
	ds_read_b128 v[32:35], v4 offset:7168
	s_waitcnt lgkmcnt(7)
	v_pk_add_f32 v[2:3], v[2:3], 0 op_sel_hi:[1,0]
	v_pk_add_f32 v[0:1], v[0:1], 0 op_sel_hi:[1,0]
	s_waitcnt lgkmcnt(6)
	v_pk_add_f32 v[2:3], v[2:3], v[8:9]
	v_pk_add_f32 v[0:1], v[0:1], v[6:7]
	s_waitcnt lgkmcnt(5)
	v_pk_add_f32 v[2:3], v[2:3], v[12:13]
	v_pk_add_f32 v[0:1], v[0:1], v[10:11]
	s_waitcnt lgkmcnt(4)
	v_pk_add_f32 v[2:3], v[2:3], v[18:19]
	v_pk_add_f32 v[0:1], v[0:1], v[16:17]
	s_waitcnt lgkmcnt(3)
	v_pk_add_f32 v[2:3], v[2:3], v[22:23]
	v_pk_add_f32 v[0:1], v[0:1], v[20:21]
	s_waitcnt lgkmcnt(2)
	v_pk_add_f32 v[2:3], v[2:3], v[26:27]
	v_pk_add_f32 v[0:1], v[0:1], v[24:25]
	s_waitcnt lgkmcnt(1)
	v_pk_add_f32 v[2:3], v[2:3], v[30:31]
	v_pk_add_f32 v[0:1], v[0:1], v[28:29]
	s_waitcnt lgkmcnt(0)
	v_pk_add_f32 v[2:3], v[2:3], v[34:35]
	v_pk_add_f32 v[0:1], v[0:1], v[32:33]
	s_waitcnt vmcnt(0)
	v_lshlrev_b32_e32 v6, 16, v38
	v_and_b32_e32 v7, 0xffff0000, v38
	v_lshlrev_b32_e32 v8, 16, v39
	v_and_b32_e32 v9, 0xffff0000, v39
	v_pk_add_f32 v[0:1], v[0:1], v[6:7]
	v_pk_add_f32 v[2:3], v[2:3], v[8:9]
	v_lshl_add_u64 v[6:7], v[36:37], 2, s[48:49]
	global_store_dwordx4 v[6:7], v[0:3], off sc1

; __device__ __forceinline__ float shfl_xor_f(float v, int mask) { const int l = lane_fresh(); return __int_as_float(__builtin_amdgcn_ds_bpermute((l ^ mask) << 2, __float_as_int(v))); }
; __device__ __forceinline__ unsigned xb_add(unsigned* p, unsigned v) { return __hip_atomic_fetch_add(p, v, __ATOMIC_RELAXED, __HIP_MEMORY_SCOPE_AGENT); }
; __device__ __forceinline__ void phaseG(const Params& p, const int wv, const int rep, unsigned* bar, const bool fused) {
;     ...
;       if (tid == 0) last_l[0] = (xb_add(&CNTS[mt * 16], 1u) == 31u) ? 1u : 0u;
;       __syncthreads();
;       if (last_l[0]) {
;         __builtin_amdgcn_fence(__ATOMIC_ACQUIRE, "agent");
;         const int r = tid >> 5, c32 = tid & 31;
;         float* yrow = p.out + O_Y + (size_t)(TP + mt * 16 + r) * 1024;
;         float sq = __hip_atomic_load(XSS + (size_t)(mt * 16 + r) * 64 + c32 * 2, __ATOMIC_RELAXED, __HIP_MEMORY_SCOPE_AGENT)
;                  + __hip_atomic_load(XSS + (size_t)(mt * 16 + r) * 64 + c32 * 2 + 1, __ATOMIC_RELAXED, __HIP_MEMORY_SCOPE_AGENT);
;         sq += shfl_xor_f(sq, 16); sq += shfl_xor_f(sq, 8); sq += shfl_xor_f(sq, 4); sq += shfl_xor_f(sq, 2); sq += shfl_xor_f(sq, 1);
;         const float rs = rsqrtf(sq * (1.f / 1024.f) + EPS);
; #pragma unroll
;         for (int i = 0; i < 8; ++i) {
;           const int col = i * 128 + c32 * 4;
;           f32x4 v = *(const f32x4*)(yrow + col);
;           *(f32x4*)(yrow + col) = v * rs * *(const f32x4*)(wfin + col);
;         }
;       }
.LBB0_1200:
	s_or_b64 exec, exec, s[24:25]
	s_waitcnt lgkmcnt(0)
	s_barrier
	ds_read_b32 v2, v15 offset:32768
	s_waitcnt lgkmcnt(0)
	v_cmp_eq_u32_e32 vcc, 0, v2
	s_cbranch_vccnz .LBB0_1182
	v_ashrrev_i32_e32 v2, 5, v1
	v_and_b32_e32 v3, 31, v0
	v_add_u32_e32 v0, s22, v2
	v_ashrrev_i32_e32 v1, 31, v0
	v_lshlrev_b64 v[0:1], 8, v[0:1]
	v_lshl_add_u64 v[0:1], s[10:11], 0, v[0:1]
	v_lshlrev_b32_e32 v4, 3, v3
	v_lshl_add_u64 v[0:1], v[0:1], 0, v[4:5]
	s_waitcnt vmcnt(0)
	buffer_inv sc1
	global_load_dword v10, v[0:1], off sc1
	global_load_dword v11, v[0:1], off offset:4 sc1
	v_add_u32_e32 v0, s20, v2
	v_ashrrev_i32_e32 v1, 31, v0
	v_lshlrev_b64 v[0:1], 12, v[0:1]
	v_lshl_add_u64 v[0:1], s[48:49], 0, v[0:1]
	v_lshlrev_b32_e32 v4, 4, v3
	v_lshl_add_u64 v[16:17], v[0:1], 0, v[4:5]
	v_mbcnt_lo_u32_b32 v12, -1, 0
	v_mbcnt_hi_u32_b32 v12, -1, v12
	v_mbcnt_lo_u32_b32 v13, -1, 0
	v_mbcnt_hi_u32_b32 v13, -1, v13
	v_mbcnt_lo_u32_b32 v18, -1, 0
	v_mbcnt_hi_u32_b32 v18, -1, v18
	v_mbcnt_lo_u32_b32 v19, -1, 0
	v_mbcnt_hi_u32_b32 v19, -1, v19
	v_mbcnt_lo_u32_b32 v20, -1, 0
	v_mbcnt_hi_u32_b32 v20, -1, v20
	global_load_dwordx4 v[0:3], v[16:17], off
	global_load_dwordx4 v[6:9], v4, s[46:47]
	v_lshlrev_b32_e32 v12, 2, v12
	v_xor_b32_e32 v12, 64, v12
	s_waitcnt vmcnt(2)
	v_add_f32_e32 v10, v11, v10
	ds_bpermute_b32 v11, v12, v10
	v_lshlrev_b32_e32 v12, 2, v13
	v_xor_b32_e32 v12, 32, v12
	s_waitcnt lgkmcnt(0)
	v_add_f32_e32 v10, v10, v11
	ds_bpermute_b32 v11, v12, v10
	v_lshlrev_b32_e32 v12, 2, v18
	v_xor_b32_e32 v12, 16, v12
	s_waitcnt lgkmcnt(0)
	v_add_f32_e32 v10, v10, v11
	ds_bpermute_b32 v11, v12, v10
	v_lshlrev_b32_e32 v12, 2, v19
	v_xor_b32_e32 v12, 8, v12
	s_waitcnt lgkmcnt(0)
	v_add_f32_e32 v10, v10, v11
	ds_bpermute_b32 v11, v12, v10
	v_lshlrev_b32_e32 v12, 2, v20
	v_xor_b32_e32 v12, 4, v12
	s_waitcnt lgkmcnt(0)
	v_add_f32_e32 v10, v10, v11
	ds_bpermute_b32 v11, v12, v10
	s_waitcnt lgkmcnt(0)
	v_add_f32_e32 v10, v10, v11
	v_fmamk_f32 v10, v10, 0x3a800000, v14
	v_mul_f32_e32 v11, 0x4b800000, v10
	v_cmp_gt_f32_e32 vcc, s37, v10
	s_nop 1
	v_cndmask_b32_e32 v10, v10, v11, vcc
	v_rsq_f32_e32 v18, v10
	global_load_dwordx4 v[10:13], v[16:17], off offset:512
	v_mul_f32_e32 v19, 0x45800000, v18
	v_cndmask_b32_e32 v18, v18, v19, vcc
	s_waitcnt vmcnt(2)
	v_pk_mul_f32 v[0:1], v[0:1], v[18:19] op_sel_hi:[1,0]
	v_pk_mul_f32 v[2:3], v[2:3], v[18:19] op_sel_hi:[1,0]
	s_waitcnt vmcnt(1)
	v_pk_mul_f32 v[0:1], v[6:7], v[0:1]
	v_pk_mul_f32 v[2:3], v[8:9], v[2:3]
	global_store_dwordx4 v[16:17], v[0:3], off sc1
	global_load_dwordx4 v[0:3], v4, s[46:47] offset:512
	s_nop 0
	global_load_dwordx4 v[6:9], v[16:17], off offset:1024
	s_waitcnt vmcnt(3)
	v_pk_mul_f32 v[12:13], v[12:13], v[18:19] op_sel_hi:[1,0]
	v_pk_mul_f32 v[10:11], v[10:11], v[18:19] op_sel_hi:[1,0]
	s_waitcnt vmcnt(1)
	v_pk_mul_f32 v[2:3], v[2:3], v[12:13]
	v_pk_mul_f32 v[0:1], v[0:1], v[10:11]
	global_store_dwordx4 v[16:17], v[0:3], off offset:512 sc1
	global_load_dwordx4 v[0:3], v4, s[46:47] offset:1024
	s_nop 0
	global_load_dwordx4 v[10:13], v[16:17], off offset:1536
	s_waitcnt vmcnt(3)
	v_pk_mul_f32 v[8:9], v[8:9], v[18:19] op_sel_hi:[1,0]
	v_pk_mul_f32 v[6:7], v[6:7], v[18:19] op_sel_hi:[1,0]
	s_waitcnt vmcnt(1)
	v_pk_mul_f32 v[2:3], v[2:3], v[8:9]
	v_pk_mul_f32 v[0:1], v[0:1], v[6:7]
	global_store_dwordx4 v[16:17], v[0:3], off offset:1024 sc1
	global_load_dwordx4 v[0:3], v4, s[46:47] offset:1536
	s_nop 0
	global_load_dwordx4 v[6:9], v[16:17], off offset:2048
	s_waitcnt vmcnt(3)
	v_pk_mul_f32 v[12:13], v[12:13], v[18:19] op_sel_hi:[1,0]
	v_pk_mul_f32 v[10:11], v[10:11], v[18:19] op_sel_hi:[1,0]
	s_waitcnt vmcnt(1)
	v_pk_mul_f32 v[2:3], v[2:3], v[12:13]
	v_pk_mul_f32 v[0:1], v[0:1], v[10:11]
	global_store_dwordx4 v[16:17], v[0:3], off offset:1536 sc1
	global_load_dwordx4 v[0:3], v4, s[46:47] offset:2048
	s_nop 0
	global_load_dwordx4 v[10:13], v[16:17], off offset:2560
	s_waitcnt vmcnt(3)
	v_pk_mul_f32 v[8:9], v[18:19], v[8:9] op_sel_hi:[0,1]
	v_pk_mul_f32 v[6:7], v[18:19], v[6:7] op_sel_hi:[0,1]
	s_waitcnt vmcnt(1)
	v_pk_mul_f32 v[0:1], v[6:7], v[0:1]
	v_pk_mul_f32 v[2:3], v[8:9], v[2:3]
	global_store_dwordx4 v[16:17], v[0:3], off offset:2048 sc1
	global_load_dwordx4 v[0:3], v4, s[46:47] offset:2560
	s_nop 0
	global_load_dwordx4 v[6:9], v[16:17], off offset:3072
	s_waitcnt vmcnt(3)
	v_pk_mul_f32 v[12:13], v[18:19], v[12:13] op_sel_hi:[0,1]
	v_pk_mul_f32 v[10:11], v[18:19], v[10:11] op_sel_hi:[0,1]
	s_waitcnt vmcnt(1)
	v_pk_mul_f32 v[0:1], v[10:11], v[0:1]
	v_pk_mul_f32 v[2:3], v[12:13], v[2:3]
	global_store_dwordx4 v[16:17], v[0:3], off offset:2560 sc1
	global_load_dwordx4 v[0:3], v4, s[46:47] offset:3072
	s_nop 0
	global_load_dwordx4 v[10:13], v[16:17], off offset:3584
	s_waitcnt vmcnt(3)
	v_pk_mul_f32 v[8:9], v[18:19], v[8:9] op_sel_hi:[0,1]
	v_pk_mul_f32 v[6:7], v[18:19], v[6:7] op_sel_hi:[0,1]
	s_waitcnt vmcnt(1)
	v_pk_mul_f32 v[0:1], v[6:7], v[0:1]
	v_pk_mul_f32 v[2:3], v[8:9], v[2:3]
	global_store_dwordx4 v[16:17], v[0:3], off offset:3072 sc1
	global_load_dwordx4 v[0:3], v4, s[46:47] offset:3584
	s_waitcnt vmcnt(2)
	v_pk_mul_f32 v[6:7], v[18:19], v[12:13] op_sel_hi:[0,1]
	v_pk_mul_f32 v[8:9], v[18:19], v[10:11] op_sel_hi:[0,1]
	s_waitcnt vmcnt(0)
	v_pk_mul_f32 v[0:1], v[8:9], v[0:1]
	v_pk_mul_f32 v[2:3], v[6:7], v[2:3]
	global_store_dwordx4 v[16:17], v[0:3], off offset:3584 sc1
	s_branch .LBB0_1182

; __device__ __forceinline__ void phaseH(const Params& p, const int wv, const int rep) {
;     ...
;   for (int r_ = gw; r_ < T * rep; r_ += nw) {
;     const int r = r_ >= T ? r_ - T : r_;
;     float* x = p.out + O_Y + (size_t)r * 1024;
;     f32x4 v[4]; float ss = 0.f;
; #pragma unroll
;     for (int i = 0; i < 4; ++i) { v[i] = *(const f32x4*)(x + (i * 64 + lane) * 4); ss += v[i][0] * v[i][0] + v[i][1] * v[i][1] + v[i][2] * v[i][2] + v[i][3] * v[i][3]; }
;     ss = wave_sum(ss);
;     const float rstd = rsqrtf(ss * (1.f / 1024.f) + EPS);
; #pragma unroll
;     for (int i = 0; i < 4; ++i) { f32x4 wv = *(const f32x4*)(w + (i * 64 + lane) * 4); *(f32x4*)(x + (i * 64 + lane) * 4) = v[i] * rstd * wv; }
;   }
.LBB0_1259:
	global_load_dwordx4 v[6:9], v[2:3], off offset:-3072
	global_load_dwordx4 v[10:13], v[2:3], off offset:-2048
	global_load_dwordx4 v[14:17], v[2:3], off offset:-1024
	global_load_dwordx4 v[18:21], v[2:3], off
	v_mbcnt_lo_u32_b32 v5, -1, 0
	v_mbcnt_hi_u32_b32 v5, -1, v5
	v_mbcnt_lo_u32_b32 v42, -1, 0
	v_mbcnt_hi_u32_b32 v42, -1, v42
	v_mbcnt_lo_u32_b32 v43, -1, 0
	v_mbcnt_hi_u32_b32 v43, -1, v43
	v_mbcnt_lo_u32_b32 v44, -1, 0
	v_mbcnt_hi_u32_b32 v44, -1, v44
	v_mbcnt_lo_u32_b32 v45, -1, 0
	v_mbcnt_hi_u32_b32 v45, -1, v45
	v_mbcnt_lo_u32_b32 v46, -1, 0
	v_mbcnt_hi_u32_b32 v46, -1, v46
	global_load_dwordx4 v[22:25], v[0:1], off
	v_lshlrev_b32_e32 v5, 2, v5
	v_xor_b32_e32 v5, 0x80, v5
	s_add_i32 s4, s4, s6
	s_cmpk_lt_i32 s4, 0x4080
	s_waitcnt vmcnt(4)
	v_mov_b32_e32 v28, v7
	s_waitcnt vmcnt(3)
	v_mov_b32_e32 v29, v11
	v_mov_b32_e32 v26, v6
	v_mov_b32_e32 v27, v10
	s_waitcnt vmcnt(2)
	v_mov_b32_e32 v36, v15
	s_waitcnt vmcnt(1)
	v_mov_b32_e32 v37, v19
	v_pk_mul_f32 v[28:29], v[28:29], v[28:29]
	v_mov_b32_e32 v30, v8
	v_mov_b32_e32 v31, v12
	v_mov_b32_e32 v34, v14
	v_mov_b32_e32 v35, v18
	v_pk_mul_f32 v[36:37], v[36:37], v[36:37]
	v_pk_fma_f32 v[26:27], v[26:27], v[26:27], v[28:29]
	v_mov_b32_e32 v32, v9
	v_mov_b32_e32 v33, v13
	v_mov_b32_e32 v38, v16
	v_mov_b32_e32 v39, v20
	v_pk_fma_f32 v[28:29], v[34:35], v[34:35], v[36:37]
	v_pk_fma_f32 v[26:27], v[30:31], v[30:31], v[26:27]
	v_mov_b32_e32 v40, v17
	v_mov_b32_e32 v41, v21
	v_pk_fma_f32 v[28:29], v[38:39], v[38:39], v[28:29]
	v_pk_fma_f32 v[26:27], v[32:33], v[32:33], v[26:27]
	v_pk_fma_f32 v[28:29], v[40:41], v[40:41], v[28:29]
	v_add_f32_e32 v26, v26, v27
	v_add_f32_e32 v26, v26, v28
	v_add_f32_e32 v26, v26, v29
	ds_bpermute_b32 v5, v5, v26
	v_lshlrev_b32_e32 v27, 2, v42
	v_xor_b32_e32 v27, 64, v27
	s_waitcnt lgkmcnt(0)
	v_add_f32_e32 v5, v26, v5
	ds_bpermute_b32 v26, v27, v5
	v_lshlrev_b32_e32 v27, 2, v43
	v_xor_b32_e32 v27, 32, v27
	s_waitcnt lgkmcnt(0)
	v_add_f32_e32 v5, v5, v26
	ds_bpermute_b32 v26, v27, v5
	v_lshlrev_b32_e32 v27, 2, v44
	v_xor_b32_e32 v27, 16, v27
	s_waitcnt lgkmcnt(0)
	v_add_f32_e32 v5, v5, v26
	ds_bpermute_b32 v26, v27, v5
	v_lshlrev_b32_e32 v27, 2, v45
	v_xor_b32_e32 v27, 8, v27
	s_waitcnt lgkmcnt(0)
	v_add_f32_e32 v5, v5, v26
	ds_bpermute_b32 v26, v27, v5
	v_lshlrev_b32_e32 v27, 2, v46
	v_xor_b32_e32 v27, 4, v27
	s_waitcnt lgkmcnt(0)
	v_add_f32_e32 v5, v5, v26
	ds_bpermute_b32 v26, v27, v5
	s_waitcnt lgkmcnt(0)
	v_add_f32_e32 v5, v5, v26
	v_fmamk_f32 v5, v5, 0x3a800000, v4
	v_mul_f32_e32 v26, 0x4b800000, v5
	v_cmp_gt_f32_e32 vcc, s2, v5
	s_nop 1
	v_cndmask_b32_e32 v5, v5, v26, vcc
	v_rsq_f32_e32 v5, v5
	s_nop 0
	v_mul_f32_e32 v26, 0x45800000, v5
	v_cndmask_b32_e32 v26, v5, v26, vcc
	v_pk_mul_f32 v[6:7], v[6:7], v[26:27] op_sel_hi:[1,0]
	v_pk_mul_f32 v[8:9], v[8:9], v[26:27] op_sel_hi:[1,0]
	s_waitcnt vmcnt(0)
	v_pk_mul_f32 v[6:7], v[22:23], v[6:7]
	v_pk_mul_f32 v[8:9], v[24:25], v[8:9]
	global_store_dwordx4 v[2:3], v[6:9], off offset:-3072 sc1
	global_load_dwordx4 v[6:9], v[0:1], off offset:1024
	v_pk_mul_f32 v[12:13], v[12:13], v[26:27] op_sel_hi:[1,0]
	v_pk_mul_f32 v[10:11], v[10:11], v[26:27] op_sel_hi:[1,0]
	s_waitcnt vmcnt(0)
	v_pk_mul_f32 v[8:9], v[8:9], v[12:13]
	v_pk_mul_f32 v[6:7], v[6:7], v[10:11]
	global_store_dwordx4 v[2:3], v[6:9], off offset:-2048 sc1
	global_load_dwordx4 v[6:9], v[0:1], off offset:2048
	v_pk_mul_f32 v[10:11], v[16:17], v[26:27] op_sel_hi:[1,0]
	v_pk_mul_f32 v[12:13], v[14:15], v[26:27] op_sel_hi:[1,0]
	s_waitcnt vmcnt(0)
	v_pk_mul_f32 v[8:9], v[8:9], v[10:11]
	v_pk_mul_f32 v[6:7], v[6:7], v[12:13]
	global_store_dwordx4 v[2:3], v[6:9], off offset:-1024 sc1
	global_load_dwordx4 v[6:9], v[0:1], off offset:3072
	v_pk_mul_f32 v[10:11], v[20:21], v[26:27] op_sel_hi:[1,0]
	v_pk_mul_f32 v[12:13], v[18:19], v[26:27] op_sel_hi:[1,0]
	s_waitcnt vmcnt(0)
	v_pk_mul_f32 v[8:9], v[8:9], v[10:11]
	v_pk_mul_f32 v[6:7], v[6:7], v[12:13]
	global_store_dwordx4 v[2:3], v[6:9], off sc1
	v_lshl_add_u64 v[2:3], v[2:3], 0, s[0:1]
	s_cbranch_scc1 .LBB0_1259
